# v32 plus K-loop LDS-DMA loads use SGPR base plus 32-bit VGPR offset (saddr form), removing the 64-bit VALU address adds from the load segments
# speedup vs baseline: 1.0037x; 1.0037x over previous
.Lmy_prio_skip0:
.LBB0_116:
	ds_read_b128 v[128:131], v229
	ds_read_b128 v[132:135], v229 offset:1024
	ds_read_b128 v[136:139], v229 offset:2048
	ds_read_b128 v[140:143], v229 offset:3072
	ds_read_b128 v[144:147], v230
	ds_read_b128 v[148:151], v230 offset:1024
	ds_read_b128 v[152:155], v230 offset:2048
	ds_read_b128 v[156:159], v230 offset:3072
	s_add_u32 vcc_lo, s94, 0x100
	s_addc_u32 vcc_hi, s95, 0
	s_cmp_eq_u32 s37, 60
	s_cselect_b32 s53, s89, vcc_hi
	s_cselect_b32 s52, s93, vcc_lo
	s_cselect_b32 s97, s85, s36
	s_cselect_b32 s96, s34, s35
	s_add_i32 m0, s67, 0xc000
	ds_read_b128 v[160:163], v231
	ds_read_b128 v[164:167], v231 offset:1024
	ds_read_b128 v[186:189], v231 offset:2048
	ds_read_b128 v[190:193], v231 offset:3072
	ds_read_b128 v[194:197], v231 offset:4096
	ds_read_b128 v[198:201], v231 offset:5120
	ds_read_b128 v[202:205], v231 offset:6144
	ds_read_b128 v[206:209], v231 offset:7168
	global_load_lds_dwordx4 v178, s[94:95]
	s_add_i32 m0, s67, 0xe000
	s_nop 0
	global_load_lds_dwordx4 v180, s[94:95]
	s_waitcnt vmcnt(8)
	s_waitcnt lgkmcnt(0)
	s_barrier
	s_waitcnt lgkmcnt(0)
	v_mfma_f32_16x16x32_bf16 v[124:127], v[128:131], v[160:163], v[124:127]
	v_mfma_f32_16x16x32_bf16 v[120:123], v[136:139], v[160:163], v[120:123]
	v_mfma_f32_16x16x32_bf16 v[112:115], v[128:131], v[186:189], v[112:115]
	v_mfma_f32_16x16x32_bf16 v[104:107], v[136:139], v[186:189], v[104:107]
	v_mfma_f32_16x16x32_bf16 v[96:99], v[128:131], v[194:197], v[96:99]
	v_mfma_f32_16x16x32_bf16 v[88:91], v[136:139], v[194:197], v[88:91]
	v_mfma_f32_16x16x32_bf16 v[80:83], v[128:131], v[202:205], v[80:83]
	v_mfma_f32_16x16x32_bf16 v[72:75], v[136:139], v[202:205], v[72:75]
	v_mfma_f32_16x16x32_bf16 v[124:127], v[132:135], v[164:167], v[124:127]
	v_mfma_f32_16x16x32_bf16 v[120:123], v[140:143], v[164:167], v[120:123]
	v_mfma_f32_16x16x32_bf16 v[112:115], v[132:135], v[190:193], v[112:115]
	v_mfma_f32_16x16x32_bf16 v[104:107], v[140:143], v[190:193], v[104:107]
	v_mfma_f32_16x16x32_bf16 v[96:99], v[132:135], v[198:201], v[96:99]
	v_mfma_f32_16x16x32_bf16 v[88:91], v[140:143], v[198:201], v[88:91]
	v_mfma_f32_16x16x32_bf16 v[80:83], v[132:135], v[206:209], v[80:83]
	v_mfma_f32_16x16x32_bf16 v[72:75], v[140:143], v[206:209], v[72:75]
	v_mfma_f32_16x16x32_bf16 v[116:119], v[144:147], v[160:163], v[116:119]
	v_mfma_f32_16x16x32_bf16 v[108:111], v[152:155], v[160:163], v[108:111]
	v_mfma_f32_16x16x32_bf16 v[100:103], v[144:147], v[186:189], v[100:103]
	v_mfma_f32_16x16x32_bf16 v[92:95], v[152:155], v[186:189], v[92:95]
	v_mfma_f32_16x16x32_bf16 v[84:87], v[144:147], v[194:197], v[84:87]
	v_mfma_f32_16x16x32_bf16 v[76:79], v[152:155], v[194:197], v[76:79]
	v_mfma_f32_16x16x32_bf16 v[68:71], v[144:147], v[202:205], v[68:71]
	v_mfma_f32_16x16x32_bf16 v[64:67], v[152:155], v[202:205], v[64:67]
	v_mfma_f32_16x16x32_bf16 v[116:119], v[148:151], v[164:167], v[116:119]
	v_mfma_f32_16x16x32_bf16 v[108:111], v[156:159], v[164:167], v[108:111]
	v_mfma_f32_16x16x32_bf16 v[100:103], v[148:151], v[190:193], v[100:103]
	v_mfma_f32_16x16x32_bf16 v[92:95], v[156:159], v[190:193], v[92:95]
	v_mfma_f32_16x16x32_bf16 v[84:87], v[148:151], v[198:201], v[84:87]
	v_mfma_f32_16x16x32_bf16 v[76:79], v[156:159], v[198:201], v[76:79]
	v_mfma_f32_16x16x32_bf16 v[68:71], v[148:151], v[206:209], v[68:71]
	v_mfma_f32_16x16x32_bf16 v[64:67], v[156:159], v[206:209], v[64:67]
	s_barrier
	s_add_i32 s38, s81, s91
	v_lshl_add_u64 v[210:211], s[96:97], 0, v[170:171]
	s_mov_b32 m0, s38
	ds_read_b128 v[160:163], v231 offset:16384
	ds_read_b128 v[164:167], v231 offset:17408
	ds_read_b128 v[186:189], v231 offset:18432
	ds_read_b128 v[190:193], v231 offset:19456
	ds_read_b128 v[194:197], v231 offset:20480
	ds_read_b128 v[198:201], v231 offset:21504
	ds_read_b128 v[202:205], v231 offset:22528
	ds_read_b128 v[206:209], v231 offset:23552
	global_load_lds_dwordx4 v170, s[96:97]
	s_add_i32 m0, s38, 0x2000
	s_add_u32 s38, s96, 0x100000
	v_lshl_add_u64 v[212:213], s[96:97], 0, v[174:175]
	s_addc_u32 s39, s97, 0
	s_add_i32 s40, s14, s91
	global_load_lds_dwordx4 v174, s[96:97]
	s_mov_b32 m0, s40
	v_lshl_add_u64 v[216:217], s[52:53], 0, v[172:173]
	global_load_lds_dwordx4 v170, s[38:39]
	s_add_i32 m0, s40, 0x2000
	s_nop 0
	global_load_lds_dwordx4 v174, s[38:39]
	v_lshl_add_u64 v[214:215], s[52:53], 0, v[168:169]
	s_mov_b32 m0, s67
	s_nop 0
	global_load_lds_dwordx4 v168, s[52:53]
	s_mov_b32 m0, s16
	s_nop 0
	global_load_lds_dwordx4 v172, s[52:53]
	s_waitcnt vmcnt(8)
	s_waitcnt lgkmcnt(0)
	s_barrier
	s_waitcnt lgkmcnt(0)
	v_mfma_f32_16x16x32_bf16 v[60:63], v[128:131], v[160:163], v[60:63]
	v_mfma_f32_16x16x32_bf16 v[56:59], v[136:139], v[160:163], v[56:59]
	v_mfma_f32_16x16x32_bf16 v[44:47], v[128:131], v[186:189], v[44:47]
	v_mfma_f32_16x16x32_bf16 v[40:43], v[136:139], v[186:189], v[40:43]
	v_mfma_f32_16x16x32_bf16 v[28:31], v[128:131], v[194:197], v[28:31]
	v_mfma_f32_16x16x32_bf16 v[24:27], v[136:139], v[194:197], v[24:27]
	v_mfma_f32_16x16x32_bf16 v[12:15], v[128:131], v[202:205], v[12:15]
	v_mfma_f32_16x16x32_bf16 v[8:11], v[136:139], v[202:205], v[8:11]
	v_mfma_f32_16x16x32_bf16 v[60:63], v[132:135], v[164:167], v[60:63]
	v_mfma_f32_16x16x32_bf16 v[56:59], v[140:143], v[164:167], v[56:59]
	v_mfma_f32_16x16x32_bf16 v[44:47], v[132:135], v[190:193], v[44:47]
	v_mfma_f32_16x16x32_bf16 v[40:43], v[140:143], v[190:193], v[40:43]
	v_mfma_f32_16x16x32_bf16 v[28:31], v[132:135], v[198:201], v[28:31]
	v_mfma_f32_16x16x32_bf16 v[24:27], v[140:143], v[198:201], v[24:27]
	v_mfma_f32_16x16x32_bf16 v[12:15], v[132:135], v[206:209], v[12:15]
	v_mfma_f32_16x16x32_bf16 v[8:11], v[140:143], v[206:209], v[8:11]
	v_mfma_f32_16x16x32_bf16 v[52:55], v[144:147], v[160:163], v[52:55]
	v_mfma_f32_16x16x32_bf16 v[48:51], v[152:155], v[160:163], v[48:51]
	v_mfma_f32_16x16x32_bf16 v[36:39], v[144:147], v[186:189], v[36:39]
	v_mfma_f32_16x16x32_bf16 v[32:35], v[152:155], v[186:189], v[32:35]
	v_mfma_f32_16x16x32_bf16 v[20:23], v[144:147], v[194:197], v[20:23]
	v_mfma_f32_16x16x32_bf16 v[16:19], v[152:155], v[194:197], v[16:19]
	v_mfma_f32_16x16x32_bf16 v[4:7], v[144:147], v[202:205], v[4:7]
	v_mfma_f32_16x16x32_bf16 v[0:3], v[152:155], v[202:205], v[0:3]
	v_mfma_f32_16x16x32_bf16 v[52:55], v[148:151], v[164:167], v[52:55]
	v_mfma_f32_16x16x32_bf16 v[48:51], v[156:159], v[164:167], v[48:51]
	v_mfma_f32_16x16x32_bf16 v[36:39], v[148:151], v[190:193], v[36:39]
	v_mfma_f32_16x16x32_bf16 v[32:35], v[156:159], v[190:193], v[32:35]
	v_mfma_f32_16x16x32_bf16 v[20:23], v[148:151], v[198:201], v[20:23]
	v_mfma_f32_16x16x32_bf16 v[16:19], v[156:159], v[198:201], v[16:19]
	v_mfma_f32_16x16x32_bf16 v[4:7], v[148:151], v[206:209], v[4:7]
	v_mfma_f32_16x16x32_bf16 v[0:3], v[156:159], v[206:209], v[0:3]
	s_barrier
	s_add_i32 s40, 0, 0x18000
	s_add_i32 s41, 0, 0x1c000
	v_add_u32_e32 v140, s40, v225
	v_add_u32_e32 v156, s41, v225
	ds_read_b128 v[128:131], v140
	ds_read_b128 v[132:135], v140 offset:1024
	ds_read_b128 v[136:139], v140 offset:2048
	ds_read_b128 v[140:143], v140 offset:3072
	ds_read_b128 v[144:147], v156
	ds_read_b128 v[148:151], v156 offset:1024
	ds_read_b128 v[152:155], v156 offset:2048
	ds_read_b128 v[156:159], v156 offset:3072
	s_add_u32 s38, s52, 0x100000
	s_addc_u32 s39, s53, 0
	s_mov_b32 m0, s17
	ds_read_b128 v[160:163], v231 offset:32768
	ds_read_b128 v[164:167], v231 offset:33792
	ds_read_b128 v[186:189], v231 offset:34816
	ds_read_b128 v[190:193], v231 offset:35840
	ds_read_b128 v[194:197], v231 offset:36864
	ds_read_b128 v[198:201], v231 offset:37888
	ds_read_b128 v[202:205], v231 offset:38912
	ds_read_b128 v[206:209], v231 offset:39936
	global_load_lds_dwordx4 v168, s[38:39]
	s_mov_b32 m0, s10
	s_nop 0
	global_load_lds_dwordx4 v172, s[38:39]
	s_waitcnt vmcnt(8)
	s_waitcnt lgkmcnt(0)
	s_barrier
	s_waitcnt lgkmcnt(0)
	v_mfma_f32_16x16x32_bf16 v[124:127], v[128:131], v[160:163], v[124:127]
	v_mfma_f32_16x16x32_bf16 v[120:123], v[136:139], v[160:163], v[120:123]
	v_mfma_f32_16x16x32_bf16 v[112:115], v[128:131], v[186:189], v[112:115]
	v_mfma_f32_16x16x32_bf16 v[104:107], v[136:139], v[186:189], v[104:107]
	v_mfma_f32_16x16x32_bf16 v[96:99], v[128:131], v[194:197], v[96:99]
	v_mfma_f32_16x16x32_bf16 v[88:91], v[136:139], v[194:197], v[88:91]
	v_mfma_f32_16x16x32_bf16 v[80:83], v[128:131], v[202:205], v[80:83]
	v_mfma_f32_16x16x32_bf16 v[72:75], v[136:139], v[202:205], v[72:75]
	v_mfma_f32_16x16x32_bf16 v[124:127], v[132:135], v[164:167], v[124:127]
	v_mfma_f32_16x16x32_bf16 v[120:123], v[140:143], v[164:167], v[120:123]
	v_mfma_f32_16x16x32_bf16 v[112:115], v[132:135], v[190:193], v[112:115]
	v_mfma_f32_16x16x32_bf16 v[104:107], v[140:143], v[190:193], v[104:107]
	v_mfma_f32_16x16x32_bf16 v[96:99], v[132:135], v[198:201], v[96:99]
	v_mfma_f32_16x16x32_bf16 v[88:91], v[140:143], v[198:201], v[88:91]
	v_mfma_f32_16x16x32_bf16 v[80:83], v[132:135], v[206:209], v[80:83]
	v_mfma_f32_16x16x32_bf16 v[72:75], v[140:143], v[206:209], v[72:75]
	v_mfma_f32_16x16x32_bf16 v[116:119], v[144:147], v[160:163], v[116:119]
	v_mfma_f32_16x16x32_bf16 v[108:111], v[152:155], v[160:163], v[108:111]
	v_mfma_f32_16x16x32_bf16 v[100:103], v[144:147], v[186:189], v[100:103]
	v_mfma_f32_16x16x32_bf16 v[92:95], v[152:155], v[186:189], v[92:95]
	v_mfma_f32_16x16x32_bf16 v[84:87], v[144:147], v[194:197], v[84:87]
	v_mfma_f32_16x16x32_bf16 v[76:79], v[152:155], v[194:197], v[76:79]
	v_mfma_f32_16x16x32_bf16 v[68:71], v[144:147], v[202:205], v[68:71]
	v_mfma_f32_16x16x32_bf16 v[64:67], v[152:155], v[202:205], v[64:67]
	v_mfma_f32_16x16x32_bf16 v[116:119], v[148:151], v[164:167], v[116:119]
	v_mfma_f32_16x16x32_bf16 v[108:111], v[156:159], v[164:167], v[108:111]
	v_mfma_f32_16x16x32_bf16 v[100:103], v[148:151], v[190:193], v[100:103]
	v_mfma_f32_16x16x32_bf16 v[92:95], v[156:159], v[190:193], v[92:95]
	v_mfma_f32_16x16x32_bf16 v[84:87], v[148:151], v[198:201], v[84:87]
	v_mfma_f32_16x16x32_bf16 v[76:79], v[156:159], v[198:201], v[76:79]
	v_mfma_f32_16x16x32_bf16 v[68:71], v[148:151], v[206:209], v[68:71]
	v_mfma_f32_16x16x32_bf16 v[64:67], v[156:159], v[206:209], v[64:67]
	s_barrier
	s_add_i32 s38, s40, s91
	v_lshl_add_u64 v[210:211], v[210:211], 0, s[56:57]
	s_mov_b32 m0, s38
	ds_read_b128 v[160:163], v231 offset:49152
	ds_read_b128 v[164:167], v231 offset:50176
	ds_read_b128 v[186:189], v231 offset:51200
	ds_read_b128 v[190:193], v231 offset:52224
	ds_read_b128 v[194:197], v231 offset:53248
	ds_read_b128 v[198:201], v231 offset:54272
	ds_read_b128 v[202:205], v231 offset:55296
	ds_read_b128 v[206:209], v231 offset:56320
	global_load_lds_dwordx4 v[210:211], off
	s_add_i32 m0, s38, 0x2000
	s_add_u32 s38, s96, 0x100080
	v_lshl_add_u64 v[210:211], v[212:213], 0, s[56:57]
	s_addc_u32 s39, s97, 0
	s_add_i32 s40, s41, s91
	global_load_lds_dwordx4 v[210:211], off
	s_mov_b32 m0, s40
	s_nop 0
	global_load_lds_dwordx4 v170, s[38:39]
	s_add_i32 m0, s40, 0x2000
	s_nop 0
	global_load_lds_dwordx4 v174, s[38:39]
	v_lshl_add_u64 v[210:211], v[214:215], 0, s[56:57]
	s_mov_b32 m0, s13
	s_nop 0
	global_load_lds_dwordx4 v[210:211], off
	v_lshl_add_u64 v[210:211], v[216:217], 0, s[56:57]
	s_mov_b32 m0, s77
	s_nop 0
	global_load_lds_dwordx4 v[210:211], off
	s_waitcnt vmcnt(8)
	s_waitcnt lgkmcnt(0)
	s_barrier
	s_waitcnt lgkmcnt(0)
	v_mfma_f32_16x16x32_bf16 v[60:63], v[128:131], v[160:163], v[60:63]
	v_mfma_f32_16x16x32_bf16 v[56:59], v[136:139], v[160:163], v[56:59]
	v_mfma_f32_16x16x32_bf16 v[44:47], v[128:131], v[186:189], v[44:47]
	v_mfma_f32_16x16x32_bf16 v[40:43], v[136:139], v[186:189], v[40:43]
	v_mfma_f32_16x16x32_bf16 v[28:31], v[128:131], v[194:197], v[28:31]
	v_mfma_f32_16x16x32_bf16 v[24:27], v[136:139], v[194:197], v[24:27]
	v_mfma_f32_16x16x32_bf16 v[12:15], v[128:131], v[202:205], v[12:15]
	v_mfma_f32_16x16x32_bf16 v[8:11], v[136:139], v[202:205], v[8:11]
	v_mfma_f32_16x16x32_bf16 v[60:63], v[132:135], v[164:167], v[60:63]
	v_mfma_f32_16x16x32_bf16 v[56:59], v[140:143], v[164:167], v[56:59]
	v_mfma_f32_16x16x32_bf16 v[44:47], v[132:135], v[190:193], v[44:47]
	v_mfma_f32_16x16x32_bf16 v[40:43], v[140:143], v[190:193], v[40:43]
	v_mfma_f32_16x16x32_bf16 v[28:31], v[132:135], v[198:201], v[28:31]
	v_mfma_f32_16x16x32_bf16 v[24:27], v[140:143], v[198:201], v[24:27]
	v_mfma_f32_16x16x32_bf16 v[12:15], v[132:135], v[206:209], v[12:15]
	v_mfma_f32_16x16x32_bf16 v[8:11], v[140:143], v[206:209], v[8:11]
	v_mfma_f32_16x16x32_bf16 v[52:55], v[144:147], v[160:163], v[52:55]
	v_mfma_f32_16x16x32_bf16 v[48:51], v[152:155], v[160:163], v[48:51]
	v_mfma_f32_16x16x32_bf16 v[36:39], v[144:147], v[186:189], v[36:39]
	v_mfma_f32_16x16x32_bf16 v[32:35], v[152:155], v[186:189], v[32:35]
	v_mfma_f32_16x16x32_bf16 v[20:23], v[144:147], v[194:197], v[20:23]
	v_mfma_f32_16x16x32_bf16 v[16:19], v[152:155], v[194:197], v[16:19]
	v_mfma_f32_16x16x32_bf16 v[4:7], v[144:147], v[202:205], v[4:7]
	v_mfma_f32_16x16x32_bf16 v[0:3], v[152:155], v[202:205], v[0:3]
	v_mfma_f32_16x16x32_bf16 v[52:55], v[148:151], v[164:167], v[52:55]
	v_mfma_f32_16x16x32_bf16 v[48:51], v[156:159], v[164:167], v[48:51]
	v_mfma_f32_16x16x32_bf16 v[36:39], v[148:151], v[190:193], v[36:39]
	v_mfma_f32_16x16x32_bf16 v[32:35], v[156:159], v[190:193], v[32:35]
	v_mfma_f32_16x16x32_bf16 v[20:23], v[148:151], v[198:201], v[20:23]
	v_mfma_f32_16x16x32_bf16 v[16:19], v[156:159], v[198:201], v[16:19]
	v_mfma_f32_16x16x32_bf16 v[4:7], v[148:151], v[206:209], v[4:7]
	v_mfma_f32_16x16x32_bf16 v[0:3], v[156:159], v[206:209], v[0:3]
	s_barrier
	s_add_i32 s37, s37, 2
	s_add_u32 s35, s35, 0x100
	s_addc_u32 s36, s36, 0
	s_cmp_gt_u32 s37, 61
	s_mov_b64 s[94:95], vcc
	s_cbranch_scc0 .LBB0_116
	s_setprio 0
	s_and_b64 vcc, exec, s[64:65]
	s_cbranch_vccz .LBB0_119
	s_barrier

.Lmy_prio_skip1:
.LBB0_521:
	ds_read_b128 v[152:155], v149
	ds_read_b128 v[156:159], v149 offset:1024
	ds_read_b128 v[160:163], v149 offset:2048
	ds_read_b128 v[164:167], v149 offset:3072
	ds_read_b128 v[168:171], v150
	ds_read_b128 v[172:175], v150 offset:1024
	ds_read_b128 v[176:179], v150 offset:2048
	ds_read_b128 v[180:183], v150 offset:3072
	s_add_u32 s37, s46, 0xfff80080
	s_addc_u32 s38, s47, -1
	s_cmp_eq_u32 s36, 28
	s_cselect_b32 s51, s13, s38
	s_cselect_b32 s50, s64, s37
	s_cselect_b32 s49, s11, s35
	s_cselect_b32 s48, s65, s34
	s_add_i32 m0, s17, 0xc000
	ds_read_b128 v[184:187], v151
	ds_read_b128 v[188:191], v151 offset:1024
	ds_read_b128 v[192:195], v151 offset:2048
	ds_read_b128 v[196:199], v151 offset:3072
	ds_read_b128 v[200:203], v151 offset:4096
	ds_read_b128 v[204:207], v151 offset:5120
	ds_read_b128 v[208:211], v151 offset:6144
	ds_read_b128 v[212:215], v151 offset:7168
	global_load_lds_dwordx4 v136, s[46:47]
	s_add_i32 m0, s17, 0xe000
	s_nop 0
	global_load_lds_dwordx4 v138, s[46:47]
	s_waitcnt vmcnt(8)
	s_waitcnt lgkmcnt(0)
	s_barrier
	s_waitcnt lgkmcnt(0)
	v_mfma_f32_16x16x32_bf16 v[124:127], v[152:155], v[184:187], v[124:127]
	v_mfma_f32_16x16x32_bf16 v[120:123], v[160:163], v[184:187], v[120:123]
	v_mfma_f32_16x16x32_bf16 v[116:119], v[152:155], v[192:195], v[116:119]
	v_mfma_f32_16x16x32_bf16 v[108:111], v[160:163], v[192:195], v[108:111]
	v_mfma_f32_16x16x32_bf16 v[100:103], v[152:155], v[200:203], v[100:103]
	v_mfma_f32_16x16x32_bf16 v[92:95], v[160:163], v[200:203], v[92:95]
	v_mfma_f32_16x16x32_bf16 v[84:87], v[152:155], v[208:211], v[84:87]
	v_mfma_f32_16x16x32_bf16 v[76:79], v[160:163], v[208:211], v[76:79]
	v_mfma_f32_16x16x32_bf16 v[124:127], v[156:159], v[188:191], v[124:127]
	v_mfma_f32_16x16x32_bf16 v[120:123], v[164:167], v[188:191], v[120:123]
	v_mfma_f32_16x16x32_bf16 v[116:119], v[156:159], v[196:199], v[116:119]
	v_mfma_f32_16x16x32_bf16 v[108:111], v[164:167], v[196:199], v[108:111]
	v_mfma_f32_16x16x32_bf16 v[100:103], v[156:159], v[204:207], v[100:103]
	v_mfma_f32_16x16x32_bf16 v[92:95], v[164:167], v[204:207], v[92:95]
	v_mfma_f32_16x16x32_bf16 v[84:87], v[156:159], v[212:215], v[84:87]
	v_mfma_f32_16x16x32_bf16 v[76:79], v[164:167], v[212:215], v[76:79]
	v_mfma_f32_16x16x32_bf16 v[112:115], v[168:171], v[184:187], v[112:115]
	v_mfma_f32_16x16x32_bf16 v[104:107], v[176:179], v[184:187], v[104:107]
	v_mfma_f32_16x16x32_bf16 v[96:99], v[168:171], v[192:195], v[96:99]
	v_mfma_f32_16x16x32_bf16 v[88:91], v[176:179], v[192:195], v[88:91]
	v_mfma_f32_16x16x32_bf16 v[80:83], v[168:171], v[200:203], v[80:83]
	v_mfma_f32_16x16x32_bf16 v[72:75], v[176:179], v[200:203], v[72:75]
	v_mfma_f32_16x16x32_bf16 v[68:71], v[168:171], v[208:211], v[68:71]
	v_mfma_f32_16x16x32_bf16 v[64:67], v[176:179], v[208:211], v[64:67]
	v_mfma_f32_16x16x32_bf16 v[112:115], v[172:175], v[188:191], v[112:115]
	v_mfma_f32_16x16x32_bf16 v[104:107], v[180:183], v[188:191], v[104:107]
	v_mfma_f32_16x16x32_bf16 v[96:99], v[172:175], v[196:199], v[96:99]
	v_mfma_f32_16x16x32_bf16 v[88:91], v[180:183], v[196:199], v[88:91]
	v_mfma_f32_16x16x32_bf16 v[80:83], v[172:175], v[204:207], v[80:83]
	v_mfma_f32_16x16x32_bf16 v[72:75], v[180:183], v[204:207], v[72:75]
	v_mfma_f32_16x16x32_bf16 v[68:71], v[172:175], v[212:215], v[68:71]
	v_mfma_f32_16x16x32_bf16 v[64:67], v[180:183], v[212:215], v[64:67]
	s_barrier
	s_add_i32 s37, s61, s53
	s_mov_b32 m0, s37
	ds_read_b128 v[184:187], v151 offset:16384
	ds_read_b128 v[188:191], v151 offset:17408
	ds_read_b128 v[192:195], v151 offset:18432
	ds_read_b128 v[196:199], v151 offset:19456
	ds_read_b128 v[200:203], v151 offset:20480
	ds_read_b128 v[204:207], v151 offset:21504
	ds_read_b128 v[208:211], v151 offset:22528
	ds_read_b128 v[212:215], v151 offset:23552
	global_load_lds_dwordx4 v130, s[48:49]
	s_add_i32 m0, s37, 0x2000
	s_add_u32 s38, s48, 0x80000
	s_addc_u32 s39, s49, 0
	s_add_i32 s37, s62, s53
	global_load_lds_dwordx4 v134, s[48:49]
	s_mov_b32 m0, s37
	global_load_lds_dwordx4 v130, s[38:39]
	s_add_i32 m0, s37, 0x2000
	s_nop 0
	global_load_lds_dwordx4 v134, s[38:39]
	s_mov_b32 m0, s17
	s_nop 0
	global_load_lds_dwordx4 v128, s[50:51]
	s_mov_b32 m0, s54
	s_nop 0
	global_load_lds_dwordx4 v132, s[50:51]
	s_waitcnt vmcnt(8)
	s_waitcnt lgkmcnt(0)
	s_barrier
	s_waitcnt lgkmcnt(0)
	v_mfma_f32_16x16x32_bf16 v[60:63], v[152:155], v[184:187], v[60:63]
	v_mfma_f32_16x16x32_bf16 v[56:59], v[160:163], v[184:187], v[56:59]
	v_mfma_f32_16x16x32_bf16 v[52:55], v[152:155], v[192:195], v[52:55]
	v_mfma_f32_16x16x32_bf16 v[44:47], v[160:163], v[192:195], v[44:47]
	v_mfma_f32_16x16x32_bf16 v[36:39], v[152:155], v[200:203], v[36:39]
	v_mfma_f32_16x16x32_bf16 v[28:31], v[160:163], v[200:203], v[28:31]
	v_mfma_f32_16x16x32_bf16 v[20:23], v[152:155], v[208:211], v[20:23]
	v_mfma_f32_16x16x32_bf16 v[12:15], v[160:163], v[208:211], v[12:15]
	v_mfma_f32_16x16x32_bf16 v[60:63], v[156:159], v[188:191], v[60:63]
	v_mfma_f32_16x16x32_bf16 v[56:59], v[164:167], v[188:191], v[56:59]
	v_mfma_f32_16x16x32_bf16 v[52:55], v[156:159], v[196:199], v[52:55]
	v_mfma_f32_16x16x32_bf16 v[44:47], v[164:167], v[196:199], v[44:47]
	v_mfma_f32_16x16x32_bf16 v[36:39], v[156:159], v[204:207], v[36:39]
	v_mfma_f32_16x16x32_bf16 v[28:31], v[164:167], v[204:207], v[28:31]
	v_mfma_f32_16x16x32_bf16 v[20:23], v[156:159], v[212:215], v[20:23]
	v_mfma_f32_16x16x32_bf16 v[12:15], v[164:167], v[212:215], v[12:15]
	v_mfma_f32_16x16x32_bf16 v[48:51], v[168:171], v[184:187], v[48:51]
	v_mfma_f32_16x16x32_bf16 v[40:43], v[176:179], v[184:187], v[40:43]
	v_mfma_f32_16x16x32_bf16 v[32:35], v[168:171], v[192:195], v[32:35]
	v_mfma_f32_16x16x32_bf16 v[24:27], v[176:179], v[192:195], v[24:27]
	v_mfma_f32_16x16x32_bf16 v[16:19], v[168:171], v[200:203], v[16:19]
	v_mfma_f32_16x16x32_bf16 v[8:11], v[176:179], v[200:203], v[8:11]
	v_mfma_f32_16x16x32_bf16 v[4:7], v[168:171], v[208:211], v[4:7]
	v_mfma_f32_16x16x32_bf16 v[0:3], v[176:179], v[208:211], v[0:3]
	v_mfma_f32_16x16x32_bf16 v[48:51], v[172:175], v[188:191], v[48:51]
	v_mfma_f32_16x16x32_bf16 v[40:43], v[180:183], v[188:191], v[40:43]
	v_mfma_f32_16x16x32_bf16 v[32:35], v[172:175], v[196:199], v[32:35]
	v_mfma_f32_16x16x32_bf16 v[24:27], v[180:183], v[196:199], v[24:27]
	v_mfma_f32_16x16x32_bf16 v[16:19], v[172:175], v[204:207], v[16:19]
	v_mfma_f32_16x16x32_bf16 v[8:11], v[180:183], v[204:207], v[8:11]
	v_mfma_f32_16x16x32_bf16 v[4:7], v[172:175], v[212:215], v[4:7]
	v_mfma_f32_16x16x32_bf16 v[0:3], v[180:183], v[212:215], v[0:3]
	s_barrier
	s_add_i32 s37, 0, 0x18000
	s_add_i32 s40, 0, 0x1c000
	v_add_u32_e32 v164, s37, v147
	v_add_u32_e32 v180, s40, v147
	ds_read_b128 v[152:155], v164
	ds_read_b128 v[156:159], v164 offset:1024
	ds_read_b128 v[160:163], v164 offset:2048
	ds_read_b128 v[164:167], v164 offset:3072
	ds_read_b128 v[168:171], v180
	ds_read_b128 v[172:175], v180 offset:1024
	ds_read_b128 v[176:179], v180 offset:2048
	ds_read_b128 v[180:183], v180 offset:3072
	s_add_u32 s38, s50, 0x80000
	s_addc_u32 s39, s51, 0
	s_mov_b32 m0, s55
	ds_read_b128 v[184:187], v151 offset:32768
	ds_read_b128 v[188:191], v151 offset:33792
	ds_read_b128 v[192:195], v151 offset:34816
	ds_read_b128 v[196:199], v151 offset:35840
	ds_read_b128 v[200:203], v151 offset:36864
	ds_read_b128 v[204:207], v151 offset:37888
	ds_read_b128 v[208:211], v151 offset:38912
	ds_read_b128 v[212:215], v151 offset:39936
	global_load_lds_dwordx4 v128, s[38:39]
	s_mov_b32 m0, s56
	s_nop 0
	global_load_lds_dwordx4 v132, s[38:39]
	s_waitcnt vmcnt(8)
	s_waitcnt lgkmcnt(0)
	s_barrier
	s_waitcnt lgkmcnt(0)
	v_mfma_f32_16x16x32_bf16 v[124:127], v[152:155], v[184:187], v[124:127]
	v_mfma_f32_16x16x32_bf16 v[120:123], v[160:163], v[184:187], v[120:123]
	v_mfma_f32_16x16x32_bf16 v[116:119], v[152:155], v[192:195], v[116:119]
	v_mfma_f32_16x16x32_bf16 v[108:111], v[160:163], v[192:195], v[108:111]
	v_mfma_f32_16x16x32_bf16 v[100:103], v[152:155], v[200:203], v[100:103]
	v_mfma_f32_16x16x32_bf16 v[92:95], v[160:163], v[200:203], v[92:95]
	v_mfma_f32_16x16x32_bf16 v[84:87], v[152:155], v[208:211], v[84:87]
	v_mfma_f32_16x16x32_bf16 v[76:79], v[160:163], v[208:211], v[76:79]
	v_mfma_f32_16x16x32_bf16 v[124:127], v[156:159], v[188:191], v[124:127]
	v_mfma_f32_16x16x32_bf16 v[120:123], v[164:167], v[188:191], v[120:123]
	v_mfma_f32_16x16x32_bf16 v[116:119], v[156:159], v[196:199], v[116:119]
	v_mfma_f32_16x16x32_bf16 v[108:111], v[164:167], v[196:199], v[108:111]
	v_mfma_f32_16x16x32_bf16 v[100:103], v[156:159], v[204:207], v[100:103]
	v_mfma_f32_16x16x32_bf16 v[92:95], v[164:167], v[204:207], v[92:95]
	v_mfma_f32_16x16x32_bf16 v[84:87], v[156:159], v[212:215], v[84:87]
	v_mfma_f32_16x16x32_bf16 v[76:79], v[164:167], v[212:215], v[76:79]
	v_mfma_f32_16x16x32_bf16 v[112:115], v[168:171], v[184:187], v[112:115]
	v_mfma_f32_16x16x32_bf16 v[104:107], v[176:179], v[184:187], v[104:107]
	v_mfma_f32_16x16x32_bf16 v[96:99], v[168:171], v[192:195], v[96:99]
	v_mfma_f32_16x16x32_bf16 v[88:91], v[176:179], v[192:195], v[88:91]
	v_mfma_f32_16x16x32_bf16 v[80:83], v[168:171], v[200:203], v[80:83]
	v_mfma_f32_16x16x32_bf16 v[72:75], v[176:179], v[200:203], v[72:75]
	v_mfma_f32_16x16x32_bf16 v[68:71], v[168:171], v[208:211], v[68:71]
	v_mfma_f32_16x16x32_bf16 v[64:67], v[176:179], v[208:211], v[64:67]
	v_mfma_f32_16x16x32_bf16 v[112:115], v[172:175], v[188:191], v[112:115]
	v_mfma_f32_16x16x32_bf16 v[104:107], v[180:183], v[188:191], v[104:107]
	v_mfma_f32_16x16x32_bf16 v[96:99], v[172:175], v[196:199], v[96:99]
	v_mfma_f32_16x16x32_bf16 v[88:91], v[180:183], v[196:199], v[88:91]
	v_mfma_f32_16x16x32_bf16 v[80:83], v[172:175], v[204:207], v[80:83]
	v_mfma_f32_16x16x32_bf16 v[72:75], v[180:183], v[204:207], v[72:75]
	v_mfma_f32_16x16x32_bf16 v[68:71], v[172:175], v[212:215], v[68:71]
	v_mfma_f32_16x16x32_bf16 v[64:67], v[180:183], v[212:215], v[64:67]
	s_barrier
	s_add_i32 s37, s37, s53
	s_mov_b32 m0, s37
	ds_read_b128 v[184:187], v151 offset:49152
	ds_read_b128 v[188:191], v151 offset:50176
	ds_read_b128 v[192:195], v151 offset:51200
	ds_read_b128 v[196:199], v151 offset:52224
	ds_read_b128 v[200:203], v151 offset:53248
	ds_read_b128 v[204:207], v151 offset:54272
	ds_read_b128 v[208:211], v151 offset:55296
	ds_read_b128 v[212:215], v151 offset:56320
	s_add_u32 vcc_lo, s48, 0x80
	s_addc_u32 vcc_hi, s49, 0
	global_load_lds_dwordx4 v130, vcc
	s_add_i32 m0, s37, 0x2000
	s_add_u32 s38, s48, 0x80080
	s_addc_u32 s39, s49, 0
	s_add_i32 s37, s40, s53
	s_add_u32 vcc_lo, s48, 0x80
	s_addc_u32 vcc_hi, s49, 0
	global_load_lds_dwordx4 v134, vcc
	s_mov_b32 m0, s37
	s_nop 0
	global_load_lds_dwordx4 v130, s[38:39]
	s_add_i32 m0, s37, 0x2000
	s_nop 0
	global_load_lds_dwordx4 v134, s[38:39]
	s_mov_b32 m0, s58
	s_nop 0
	s_add_u32 vcc_lo, s50, 0x80
	s_addc_u32 vcc_hi, s51, 0
	global_load_lds_dwordx4 v128, vcc
	s_mov_b32 m0, s59
	s_nop 0
	s_add_u32 vcc_lo, s50, 0x80
	s_addc_u32 vcc_hi, s51, 0
	global_load_lds_dwordx4 v132, vcc
	s_waitcnt vmcnt(8)
	s_waitcnt lgkmcnt(0)
	s_barrier
	s_waitcnt lgkmcnt(0)
	v_mfma_f32_16x16x32_bf16 v[60:63], v[152:155], v[184:187], v[60:63]
	v_mfma_f32_16x16x32_bf16 v[56:59], v[160:163], v[184:187], v[56:59]
	v_mfma_f32_16x16x32_bf16 v[52:55], v[152:155], v[192:195], v[52:55]
	v_mfma_f32_16x16x32_bf16 v[44:47], v[160:163], v[192:195], v[44:47]
	v_mfma_f32_16x16x32_bf16 v[36:39], v[152:155], v[200:203], v[36:39]
	v_mfma_f32_16x16x32_bf16 v[28:31], v[160:163], v[200:203], v[28:31]
	v_mfma_f32_16x16x32_bf16 v[20:23], v[152:155], v[208:211], v[20:23]
	v_mfma_f32_16x16x32_bf16 v[12:15], v[160:163], v[208:211], v[12:15]
	v_mfma_f32_16x16x32_bf16 v[60:63], v[156:159], v[188:191], v[60:63]
	v_mfma_f32_16x16x32_bf16 v[56:59], v[164:167], v[188:191], v[56:59]
	v_mfma_f32_16x16x32_bf16 v[52:55], v[156:159], v[196:199], v[52:55]
	v_mfma_f32_16x16x32_bf16 v[44:47], v[164:167], v[196:199], v[44:47]
	v_mfma_f32_16x16x32_bf16 v[36:39], v[156:159], v[204:207], v[36:39]
	v_mfma_f32_16x16x32_bf16 v[28:31], v[164:167], v[204:207], v[28:31]
	v_mfma_f32_16x16x32_bf16 v[20:23], v[156:159], v[212:215], v[20:23]
	v_mfma_f32_16x16x32_bf16 v[12:15], v[164:167], v[212:215], v[12:15]
	v_mfma_f32_16x16x32_bf16 v[48:51], v[168:171], v[184:187], v[48:51]
	v_mfma_f32_16x16x32_bf16 v[40:43], v[176:179], v[184:187], v[40:43]
	v_mfma_f32_16x16x32_bf16 v[32:35], v[168:171], v[192:195], v[32:35]
	v_mfma_f32_16x16x32_bf16 v[24:27], v[176:179], v[192:195], v[24:27]
	v_mfma_f32_16x16x32_bf16 v[16:19], v[168:171], v[200:203], v[16:19]
	v_mfma_f32_16x16x32_bf16 v[8:11], v[176:179], v[200:203], v[8:11]
	v_mfma_f32_16x16x32_bf16 v[4:7], v[168:171], v[208:211], v[4:7]
	v_mfma_f32_16x16x32_bf16 v[0:3], v[176:179], v[208:211], v[0:3]
	v_mfma_f32_16x16x32_bf16 v[48:51], v[172:175], v[188:191], v[48:51]
	v_mfma_f32_16x16x32_bf16 v[40:43], v[180:183], v[188:191], v[40:43]
	v_mfma_f32_16x16x32_bf16 v[32:35], v[172:175], v[196:199], v[32:35]
	v_mfma_f32_16x16x32_bf16 v[24:27], v[180:183], v[196:199], v[24:27]
	v_mfma_f32_16x16x32_bf16 v[16:19], v[172:175], v[204:207], v[16:19]
	v_mfma_f32_16x16x32_bf16 v[8:11], v[180:183], v[204:207], v[8:11]
	v_mfma_f32_16x16x32_bf16 v[4:7], v[172:175], v[212:215], v[4:7]
	v_mfma_f32_16x16x32_bf16 v[0:3], v[180:183], v[212:215], v[0:3]
	s_barrier
	s_add_i32 s36, s36, 2
	s_add_u32 s46, s46, 0x100
	s_addc_u32 s47, s47, 0
	s_add_u32 s34, s34, 0x100
	s_addc_u32 s35, s35, 0
	s_cmp_gt_u32 s36, 29
	s_cbranch_scc0 .LBB0_521
	s_setprio 0
	s_and_b64 vcc, exec, s[8:9]
	s_cbranch_vccz .LBB0_524
	s_barrier

.Lmy_prio_skip2:
.LBB0_600:
	ds_read_b128 v[152:155], v149
	ds_read_b128 v[156:159], v149 offset:1024
	ds_read_b128 v[160:163], v149 offset:2048
	ds_read_b128 v[164:167], v149 offset:3072
	ds_read_b128 v[168:171], v150
	ds_read_b128 v[172:175], v150 offset:1024
	ds_read_b128 v[176:179], v150 offset:2048
	ds_read_b128 v[180:183], v150 offset:3072
	s_add_u32 s37, s48, 0xfff00080
	s_addc_u32 s38, s49, -1
	s_cmp_eq_u32 s36, 60
	s_cselect_b32 s53, s17, s38
	s_cselect_b32 s52, s66, s37
	s_cselect_b32 s51, s13, s35
	s_cselect_b32 s50, s67, s34
	s_add_i32 m0, s19, 0xc000
	ds_read_b128 v[184:187], v151
	ds_read_b128 v[188:191], v151 offset:1024
	ds_read_b128 v[192:195], v151 offset:2048
	ds_read_b128 v[196:199], v151 offset:3072
	ds_read_b128 v[200:203], v151 offset:4096
	ds_read_b128 v[204:207], v151 offset:5120
	ds_read_b128 v[208:211], v151 offset:6144
	ds_read_b128 v[212:215], v151 offset:7168
	global_load_lds_dwordx4 v136, s[48:49]
	s_add_i32 m0, s19, 0xe000
	s_nop 0
	global_load_lds_dwordx4 v138, s[48:49]
	s_waitcnt vmcnt(8)
	s_waitcnt lgkmcnt(0)
	s_barrier
	s_waitcnt lgkmcnt(0)
	v_mfma_f32_16x16x32_bf16 v[124:127], v[152:155], v[184:187], v[124:127]
	v_mfma_f32_16x16x32_bf16 v[120:123], v[160:163], v[184:187], v[120:123]
	v_mfma_f32_16x16x32_bf16 v[116:119], v[152:155], v[192:195], v[116:119]
	v_mfma_f32_16x16x32_bf16 v[108:111], v[160:163], v[192:195], v[108:111]
	v_mfma_f32_16x16x32_bf16 v[100:103], v[152:155], v[200:203], v[100:103]
	v_mfma_f32_16x16x32_bf16 v[92:95], v[160:163], v[200:203], v[92:95]
	v_mfma_f32_16x16x32_bf16 v[84:87], v[152:155], v[208:211], v[84:87]
	v_mfma_f32_16x16x32_bf16 v[76:79], v[160:163], v[208:211], v[76:79]
	v_mfma_f32_16x16x32_bf16 v[124:127], v[156:159], v[188:191], v[124:127]
	v_mfma_f32_16x16x32_bf16 v[120:123], v[164:167], v[188:191], v[120:123]
	v_mfma_f32_16x16x32_bf16 v[116:119], v[156:159], v[196:199], v[116:119]
	v_mfma_f32_16x16x32_bf16 v[108:111], v[164:167], v[196:199], v[108:111]
	v_mfma_f32_16x16x32_bf16 v[100:103], v[156:159], v[204:207], v[100:103]
	v_mfma_f32_16x16x32_bf16 v[92:95], v[164:167], v[204:207], v[92:95]
	v_mfma_f32_16x16x32_bf16 v[84:87], v[156:159], v[212:215], v[84:87]
	v_mfma_f32_16x16x32_bf16 v[76:79], v[164:167], v[212:215], v[76:79]
	v_mfma_f32_16x16x32_bf16 v[112:115], v[168:171], v[184:187], v[112:115]
	v_mfma_f32_16x16x32_bf16 v[104:107], v[176:179], v[184:187], v[104:107]
	v_mfma_f32_16x16x32_bf16 v[96:99], v[168:171], v[192:195], v[96:99]
	v_mfma_f32_16x16x32_bf16 v[88:91], v[176:179], v[192:195], v[88:91]
	v_mfma_f32_16x16x32_bf16 v[80:83], v[168:171], v[200:203], v[80:83]
	v_mfma_f32_16x16x32_bf16 v[72:75], v[176:179], v[200:203], v[72:75]
	v_mfma_f32_16x16x32_bf16 v[68:71], v[168:171], v[208:211], v[68:71]
	v_mfma_f32_16x16x32_bf16 v[64:67], v[176:179], v[208:211], v[64:67]
	v_mfma_f32_16x16x32_bf16 v[112:115], v[172:175], v[188:191], v[112:115]
	v_mfma_f32_16x16x32_bf16 v[104:107], v[180:183], v[188:191], v[104:107]
	v_mfma_f32_16x16x32_bf16 v[96:99], v[172:175], v[196:199], v[96:99]
	v_mfma_f32_16x16x32_bf16 v[88:91], v[180:183], v[196:199], v[88:91]
	v_mfma_f32_16x16x32_bf16 v[80:83], v[172:175], v[204:207], v[80:83]
	v_mfma_f32_16x16x32_bf16 v[72:75], v[180:183], v[204:207], v[72:75]
	v_mfma_f32_16x16x32_bf16 v[68:71], v[172:175], v[212:215], v[68:71]
	v_mfma_f32_16x16x32_bf16 v[64:67], v[180:183], v[212:215], v[64:67]
	s_barrier
	s_add_i32 s37, s63, s55
	s_mov_b32 m0, s37
	ds_read_b128 v[184:187], v151 offset:16384
	ds_read_b128 v[188:191], v151 offset:17408
	ds_read_b128 v[192:195], v151 offset:18432
	ds_read_b128 v[196:199], v151 offset:19456
	ds_read_b128 v[200:203], v151 offset:20480
	ds_read_b128 v[204:207], v151 offset:21504
	ds_read_b128 v[208:211], v151 offset:22528
	ds_read_b128 v[212:215], v151 offset:23552
	global_load_lds_dwordx4 v130, s[50:51]
	s_add_i32 m0, s37, 0x2000
	s_add_u32 s38, s50, 0x100000
	s_addc_u32 s39, s51, 0
	s_add_i32 s37, s64, s55
	global_load_lds_dwordx4 v134, s[50:51]
	s_mov_b32 m0, s37
	global_load_lds_dwordx4 v130, s[38:39]
	s_add_i32 m0, s37, 0x2000
	s_nop 0
	global_load_lds_dwordx4 v134, s[38:39]
	s_mov_b32 m0, s19
	s_nop 0
	global_load_lds_dwordx4 v128, s[52:53]
	s_mov_b32 m0, s56
	s_nop 0
	global_load_lds_dwordx4 v132, s[52:53]
	s_waitcnt vmcnt(8)
	s_waitcnt lgkmcnt(0)
	s_barrier
	s_waitcnt lgkmcnt(0)
	v_mfma_f32_16x16x32_bf16 v[60:63], v[152:155], v[184:187], v[60:63]
	v_mfma_f32_16x16x32_bf16 v[56:59], v[160:163], v[184:187], v[56:59]
	v_mfma_f32_16x16x32_bf16 v[52:55], v[152:155], v[192:195], v[52:55]
	v_mfma_f32_16x16x32_bf16 v[44:47], v[160:163], v[192:195], v[44:47]
	v_mfma_f32_16x16x32_bf16 v[36:39], v[152:155], v[200:203], v[36:39]
	v_mfma_f32_16x16x32_bf16 v[28:31], v[160:163], v[200:203], v[28:31]
	v_mfma_f32_16x16x32_bf16 v[20:23], v[152:155], v[208:211], v[20:23]
	v_mfma_f32_16x16x32_bf16 v[12:15], v[160:163], v[208:211], v[12:15]
	v_mfma_f32_16x16x32_bf16 v[60:63], v[156:159], v[188:191], v[60:63]
	v_mfma_f32_16x16x32_bf16 v[56:59], v[164:167], v[188:191], v[56:59]
	v_mfma_f32_16x16x32_bf16 v[52:55], v[156:159], v[196:199], v[52:55]
	v_mfma_f32_16x16x32_bf16 v[44:47], v[164:167], v[196:199], v[44:47]
	v_mfma_f32_16x16x32_bf16 v[36:39], v[156:159], v[204:207], v[36:39]
	v_mfma_f32_16x16x32_bf16 v[28:31], v[164:167], v[204:207], v[28:31]
	v_mfma_f32_16x16x32_bf16 v[20:23], v[156:159], v[212:215], v[20:23]
	v_mfma_f32_16x16x32_bf16 v[12:15], v[164:167], v[212:215], v[12:15]
	v_mfma_f32_16x16x32_bf16 v[48:51], v[168:171], v[184:187], v[48:51]
	v_mfma_f32_16x16x32_bf16 v[40:43], v[176:179], v[184:187], v[40:43]
	v_mfma_f32_16x16x32_bf16 v[32:35], v[168:171], v[192:195], v[32:35]
	v_mfma_f32_16x16x32_bf16 v[24:27], v[176:179], v[192:195], v[24:27]
	v_mfma_f32_16x16x32_bf16 v[16:19], v[168:171], v[200:203], v[16:19]
	v_mfma_f32_16x16x32_bf16 v[8:11], v[176:179], v[200:203], v[8:11]
	v_mfma_f32_16x16x32_bf16 v[4:7], v[168:171], v[208:211], v[4:7]
	v_mfma_f32_16x16x32_bf16 v[0:3], v[176:179], v[208:211], v[0:3]
	v_mfma_f32_16x16x32_bf16 v[48:51], v[172:175], v[188:191], v[48:51]
	v_mfma_f32_16x16x32_bf16 v[40:43], v[180:183], v[188:191], v[40:43]
	v_mfma_f32_16x16x32_bf16 v[32:35], v[172:175], v[196:199], v[32:35]
	v_mfma_f32_16x16x32_bf16 v[24:27], v[180:183], v[196:199], v[24:27]
	v_mfma_f32_16x16x32_bf16 v[16:19], v[172:175], v[204:207], v[16:19]
	v_mfma_f32_16x16x32_bf16 v[8:11], v[180:183], v[204:207], v[8:11]
	v_mfma_f32_16x16x32_bf16 v[4:7], v[172:175], v[212:215], v[4:7]
	v_mfma_f32_16x16x32_bf16 v[0:3], v[180:183], v[212:215], v[0:3]
	s_barrier
	s_add_i32 s37, 0, 0x18000
	s_add_i32 s40, 0, 0x1c000
	v_add_u32_e32 v164, s37, v147
	v_add_u32_e32 v180, s40, v147
	ds_read_b128 v[152:155], v164
	ds_read_b128 v[156:159], v164 offset:1024
	ds_read_b128 v[160:163], v164 offset:2048
	ds_read_b128 v[164:167], v164 offset:3072
	ds_read_b128 v[168:171], v180
	ds_read_b128 v[172:175], v180 offset:1024
	ds_read_b128 v[176:179], v180 offset:2048
	ds_read_b128 v[180:183], v180 offset:3072
	s_add_u32 s38, s52, 0x100000
	s_addc_u32 s39, s53, 0
	s_mov_b32 m0, s57
	ds_read_b128 v[184:187], v151 offset:32768
	ds_read_b128 v[188:191], v151 offset:33792
	ds_read_b128 v[192:195], v151 offset:34816
	ds_read_b128 v[196:199], v151 offset:35840
	ds_read_b128 v[200:203], v151 offset:36864
	ds_read_b128 v[204:207], v151 offset:37888
	ds_read_b128 v[208:211], v151 offset:38912
	ds_read_b128 v[212:215], v151 offset:39936
	global_load_lds_dwordx4 v128, s[38:39]
	s_mov_b32 m0, s58
	s_nop 0
	global_load_lds_dwordx4 v132, s[38:39]
	s_waitcnt vmcnt(8)
	s_waitcnt lgkmcnt(0)
	s_barrier
	s_waitcnt lgkmcnt(0)
	v_mfma_f32_16x16x32_bf16 v[124:127], v[152:155], v[184:187], v[124:127]
	v_mfma_f32_16x16x32_bf16 v[120:123], v[160:163], v[184:187], v[120:123]
	v_mfma_f32_16x16x32_bf16 v[116:119], v[152:155], v[192:195], v[116:119]
	v_mfma_f32_16x16x32_bf16 v[108:111], v[160:163], v[192:195], v[108:111]
	v_mfma_f32_16x16x32_bf16 v[100:103], v[152:155], v[200:203], v[100:103]
	v_mfma_f32_16x16x32_bf16 v[92:95], v[160:163], v[200:203], v[92:95]
	v_mfma_f32_16x16x32_bf16 v[84:87], v[152:155], v[208:211], v[84:87]
	v_mfma_f32_16x16x32_bf16 v[76:79], v[160:163], v[208:211], v[76:79]
	v_mfma_f32_16x16x32_bf16 v[124:127], v[156:159], v[188:191], v[124:127]
	v_mfma_f32_16x16x32_bf16 v[120:123], v[164:167], v[188:191], v[120:123]
	v_mfma_f32_16x16x32_bf16 v[116:119], v[156:159], v[196:199], v[116:119]
	v_mfma_f32_16x16x32_bf16 v[108:111], v[164:167], v[196:199], v[108:111]
	v_mfma_f32_16x16x32_bf16 v[100:103], v[156:159], v[204:207], v[100:103]
	v_mfma_f32_16x16x32_bf16 v[92:95], v[164:167], v[204:207], v[92:95]
	v_mfma_f32_16x16x32_bf16 v[84:87], v[156:159], v[212:215], v[84:87]
	v_mfma_f32_16x16x32_bf16 v[76:79], v[164:167], v[212:215], v[76:79]
	v_mfma_f32_16x16x32_bf16 v[112:115], v[168:171], v[184:187], v[112:115]
	v_mfma_f32_16x16x32_bf16 v[104:107], v[176:179], v[184:187], v[104:107]
	v_mfma_f32_16x16x32_bf16 v[96:99], v[168:171], v[192:195], v[96:99]
	v_mfma_f32_16x16x32_bf16 v[88:91], v[176:179], v[192:195], v[88:91]
	v_mfma_f32_16x16x32_bf16 v[80:83], v[168:171], v[200:203], v[80:83]
	v_mfma_f32_16x16x32_bf16 v[72:75], v[176:179], v[200:203], v[72:75]
	v_mfma_f32_16x16x32_bf16 v[68:71], v[168:171], v[208:211], v[68:71]
	v_mfma_f32_16x16x32_bf16 v[64:67], v[176:179], v[208:211], v[64:67]
	v_mfma_f32_16x16x32_bf16 v[112:115], v[172:175], v[188:191], v[112:115]
	v_mfma_f32_16x16x32_bf16 v[104:107], v[180:183], v[188:191], v[104:107]
	v_mfma_f32_16x16x32_bf16 v[96:99], v[172:175], v[196:199], v[96:99]
	v_mfma_f32_16x16x32_bf16 v[88:91], v[180:183], v[196:199], v[88:91]
	v_mfma_f32_16x16x32_bf16 v[80:83], v[172:175], v[204:207], v[80:83]
	v_mfma_f32_16x16x32_bf16 v[72:75], v[180:183], v[204:207], v[72:75]
	v_mfma_f32_16x16x32_bf16 v[68:71], v[172:175], v[212:215], v[68:71]
	v_mfma_f32_16x16x32_bf16 v[64:67], v[180:183], v[212:215], v[64:67]
	s_barrier
	s_add_i32 s37, s37, s55
	s_mov_b32 m0, s37
	ds_read_b128 v[184:187], v151 offset:49152
	ds_read_b128 v[188:191], v151 offset:50176
	ds_read_b128 v[192:195], v151 offset:51200
	ds_read_b128 v[196:199], v151 offset:52224
	ds_read_b128 v[200:203], v151 offset:53248
	ds_read_b128 v[204:207], v151 offset:54272
	ds_read_b128 v[208:211], v151 offset:55296
	ds_read_b128 v[212:215], v151 offset:56320
	s_add_u32 vcc_lo, s50, 0x80
	s_addc_u32 vcc_hi, s51, 0
	global_load_lds_dwordx4 v130, vcc
	s_add_i32 m0, s37, 0x2000
	s_add_u32 s38, s50, 0x100080
	s_addc_u32 s39, s51, 0
	s_add_i32 s37, s40, s55
	s_add_u32 vcc_lo, s50, 0x80
	s_addc_u32 vcc_hi, s51, 0
	global_load_lds_dwordx4 v134, vcc
	s_mov_b32 m0, s37
	s_nop 0
	global_load_lds_dwordx4 v130, s[38:39]
	s_add_i32 m0, s37, 0x2000
	s_nop 0
	global_load_lds_dwordx4 v134, s[38:39]
	s_mov_b32 m0, s60
	s_nop 0
	s_add_u32 vcc_lo, s52, 0x80
	s_addc_u32 vcc_hi, s53, 0
	global_load_lds_dwordx4 v128, vcc
	s_mov_b32 m0, s61
	s_nop 0
	s_add_u32 vcc_lo, s52, 0x80
	s_addc_u32 vcc_hi, s53, 0
	global_load_lds_dwordx4 v132, vcc
	s_waitcnt vmcnt(8)
	s_waitcnt lgkmcnt(0)
	s_barrier
	s_waitcnt lgkmcnt(0)
	v_mfma_f32_16x16x32_bf16 v[60:63], v[152:155], v[184:187], v[60:63]
	v_mfma_f32_16x16x32_bf16 v[56:59], v[160:163], v[184:187], v[56:59]
	v_mfma_f32_16x16x32_bf16 v[52:55], v[152:155], v[192:195], v[52:55]
	v_mfma_f32_16x16x32_bf16 v[44:47], v[160:163], v[192:195], v[44:47]
	v_mfma_f32_16x16x32_bf16 v[36:39], v[152:155], v[200:203], v[36:39]
	v_mfma_f32_16x16x32_bf16 v[28:31], v[160:163], v[200:203], v[28:31]
	v_mfma_f32_16x16x32_bf16 v[20:23], v[152:155], v[208:211], v[20:23]
	v_mfma_f32_16x16x32_bf16 v[12:15], v[160:163], v[208:211], v[12:15]
	v_mfma_f32_16x16x32_bf16 v[60:63], v[156:159], v[188:191], v[60:63]
	v_mfma_f32_16x16x32_bf16 v[56:59], v[164:167], v[188:191], v[56:59]
	v_mfma_f32_16x16x32_bf16 v[52:55], v[156:159], v[196:199], v[52:55]
	v_mfma_f32_16x16x32_bf16 v[44:47], v[164:167], v[196:199], v[44:47]
	v_mfma_f32_16x16x32_bf16 v[36:39], v[156:159], v[204:207], v[36:39]
	v_mfma_f32_16x16x32_bf16 v[28:31], v[164:167], v[204:207], v[28:31]
	v_mfma_f32_16x16x32_bf16 v[20:23], v[156:159], v[212:215], v[20:23]
	v_mfma_f32_16x16x32_bf16 v[12:15], v[164:167], v[212:215], v[12:15]
	v_mfma_f32_16x16x32_bf16 v[48:51], v[168:171], v[184:187], v[48:51]
	v_mfma_f32_16x16x32_bf16 v[40:43], v[176:179], v[184:187], v[40:43]
	v_mfma_f32_16x16x32_bf16 v[32:35], v[168:171], v[192:195], v[32:35]
	v_mfma_f32_16x16x32_bf16 v[24:27], v[176:179], v[192:195], v[24:27]
	v_mfma_f32_16x16x32_bf16 v[16:19], v[168:171], v[200:203], v[16:19]
	v_mfma_f32_16x16x32_bf16 v[8:11], v[176:179], v[200:203], v[8:11]
	v_mfma_f32_16x16x32_bf16 v[4:7], v[168:171], v[208:211], v[4:7]
	v_mfma_f32_16x16x32_bf16 v[0:3], v[176:179], v[208:211], v[0:3]
	v_mfma_f32_16x16x32_bf16 v[48:51], v[172:175], v[188:191], v[48:51]
	v_mfma_f32_16x16x32_bf16 v[40:43], v[180:183], v[188:191], v[40:43]
	v_mfma_f32_16x16x32_bf16 v[32:35], v[172:175], v[196:199], v[32:35]
	v_mfma_f32_16x16x32_bf16 v[24:27], v[180:183], v[196:199], v[24:27]
	v_mfma_f32_16x16x32_bf16 v[16:19], v[172:175], v[204:207], v[16:19]
	v_mfma_f32_16x16x32_bf16 v[8:11], v[180:183], v[204:207], v[8:11]
	v_mfma_f32_16x16x32_bf16 v[4:7], v[172:175], v[212:215], v[4:7]
	v_mfma_f32_16x16x32_bf16 v[0:3], v[180:183], v[212:215], v[0:3]
	s_barrier
	s_add_i32 s36, s36, 2
	s_add_u32 s48, s48, 0x100
	s_addc_u32 s49, s49, 0
	s_add_u32 s34, s34, 0x100
	s_addc_u32 s35, s35, 0
	s_cmp_gt_u32 s36, 61
	s_cbranch_scc0 .LBB0_600
	s_setprio 0
	s_and_b64 vcc, exec, s[10:11]
	s_cbranch_vccz .LBB0_603
	s_barrier

.Lmy_prio_skip3:
.LBB0_679:
	ds_read_b128 v[144:147], v151
	ds_read_b128 v[154:157], v151 offset:1024
	ds_read_b128 v[158:161], v151 offset:2048
	ds_read_b128 v[162:165], v151 offset:3072
	ds_read_b128 v[166:169], v152
	ds_read_b128 v[170:173], v152 offset:1024
	ds_read_b128 v[174:177], v152 offset:2048
	ds_read_b128 v[178:181], v152 offset:3072
	s_add_u32 s37, s50, 0xfff00080
	s_addc_u32 s38, s51, -1
	s_cmp_eq_u32 s36, 60
	s_cselect_b32 s55, s19, s38
	s_cselect_b32 s54, s66, s37
	s_cselect_b32 s53, s17, s35
	s_cselect_b32 s52, s67, s34
	s_add_i32 m0, s49, 0xc000
	ds_read_b128 v[182:185], v153
	ds_read_b128 v[186:189], v153 offset:1024
	ds_read_b128 v[190:193], v153 offset:2048
	ds_read_b128 v[194:197], v153 offset:3072
	ds_read_b128 v[198:201], v153 offset:4096
	ds_read_b128 v[202:205], v153 offset:5120
	ds_read_b128 v[206:209], v153 offset:6144
	ds_read_b128 v[210:213], v153 offset:7168
	global_load_lds_dwordx4 v136, s[50:51]
	s_add_i32 m0, s49, 0xe000
	s_nop 0
	global_load_lds_dwordx4 v138, s[50:51]
	s_waitcnt vmcnt(8)
	s_waitcnt lgkmcnt(0)
	s_barrier
	s_waitcnt lgkmcnt(0)
	v_mfma_f32_16x16x32_bf16 v[124:127], v[144:147], v[182:185], v[124:127]
	v_mfma_f32_16x16x32_bf16 v[116:119], v[158:161], v[182:185], v[116:119]
	v_mfma_f32_16x16x32_bf16 v[108:111], v[144:147], v[190:193], v[108:111]
	v_mfma_f32_16x16x32_bf16 v[104:107], v[158:161], v[190:193], v[104:107]
	v_mfma_f32_16x16x32_bf16 v[92:95], v[144:147], v[198:201], v[92:95]
	v_mfma_f32_16x16x32_bf16 v[88:91], v[158:161], v[198:201], v[88:91]
	v_mfma_f32_16x16x32_bf16 v[76:79], v[144:147], v[206:209], v[76:79]
	v_mfma_f32_16x16x32_bf16 v[72:75], v[158:161], v[206:209], v[72:75]
	v_mfma_f32_16x16x32_bf16 v[124:127], v[154:157], v[186:189], v[124:127]
	v_mfma_f32_16x16x32_bf16 v[116:119], v[162:165], v[186:189], v[116:119]
	v_mfma_f32_16x16x32_bf16 v[108:111], v[154:157], v[194:197], v[108:111]
	v_mfma_f32_16x16x32_bf16 v[104:107], v[162:165], v[194:197], v[104:107]
	v_mfma_f32_16x16x32_bf16 v[92:95], v[154:157], v[202:205], v[92:95]
	v_mfma_f32_16x16x32_bf16 v[88:91], v[162:165], v[202:205], v[88:91]
	v_mfma_f32_16x16x32_bf16 v[76:79], v[154:157], v[210:213], v[76:79]
	v_mfma_f32_16x16x32_bf16 v[72:75], v[162:165], v[210:213], v[72:75]
	v_mfma_f32_16x16x32_bf16 v[120:123], v[166:169], v[182:185], v[120:123]
	v_mfma_f32_16x16x32_bf16 v[112:115], v[174:177], v[182:185], v[112:115]
	v_mfma_f32_16x16x32_bf16 v[100:103], v[166:169], v[190:193], v[100:103]
	v_mfma_f32_16x16x32_bf16 v[96:99], v[174:177], v[190:193], v[96:99]
	v_mfma_f32_16x16x32_bf16 v[84:87], v[166:169], v[198:201], v[84:87]
	v_mfma_f32_16x16x32_bf16 v[80:83], v[174:177], v[198:201], v[80:83]
	v_mfma_f32_16x16x32_bf16 v[68:71], v[166:169], v[206:209], v[68:71]
	v_mfma_f32_16x16x32_bf16 v[64:67], v[174:177], v[206:209], v[64:67]
	v_mfma_f32_16x16x32_bf16 v[120:123], v[170:173], v[186:189], v[120:123]
	v_mfma_f32_16x16x32_bf16 v[112:115], v[178:181], v[186:189], v[112:115]
	v_mfma_f32_16x16x32_bf16 v[100:103], v[170:173], v[194:197], v[100:103]
	v_mfma_f32_16x16x32_bf16 v[96:99], v[178:181], v[194:197], v[96:99]
	v_mfma_f32_16x16x32_bf16 v[84:87], v[170:173], v[202:205], v[84:87]
	v_mfma_f32_16x16x32_bf16 v[80:83], v[178:181], v[202:205], v[80:83]
	v_mfma_f32_16x16x32_bf16 v[68:71], v[170:173], v[210:213], v[68:71]
	v_mfma_f32_16x16x32_bf16 v[64:67], v[178:181], v[210:213], v[64:67]
	s_barrier
	s_add_i32 s37, s63, s33
	s_mov_b32 m0, s37
	ds_read_b128 v[182:185], v153 offset:16384
	ds_read_b128 v[186:189], v153 offset:17408
	ds_read_b128 v[190:193], v153 offset:18432
	ds_read_b128 v[194:197], v153 offset:19456
	ds_read_b128 v[198:201], v153 offset:20480
	ds_read_b128 v[202:205], v153 offset:21504
	ds_read_b128 v[206:209], v153 offset:22528
	ds_read_b128 v[210:213], v153 offset:23552
	global_load_lds_dwordx4 v130, s[52:53]
	s_add_i32 m0, s37, 0x2000
	s_add_u32 s38, s52, 0x100000
	s_addc_u32 s39, s53, 0
	s_add_i32 s37, s64, s33
	global_load_lds_dwordx4 v134, s[52:53]
	s_mov_b32 m0, s37
	global_load_lds_dwordx4 v130, s[38:39]
	s_add_i32 m0, s37, 0x2000
	s_nop 0
	global_load_lds_dwordx4 v134, s[38:39]
	s_mov_b32 m0, s49
	s_nop 0
	global_load_lds_dwordx4 v128, s[54:55]
	s_mov_b32 m0, s56
	s_nop 0
	global_load_lds_dwordx4 v132, s[54:55]
	s_waitcnt vmcnt(8)
	s_waitcnt lgkmcnt(0)
	s_barrier
	s_waitcnt lgkmcnt(0)
	v_mfma_f32_16x16x32_bf16 v[60:63], v[144:147], v[182:185], v[60:63]
	v_mfma_f32_16x16x32_bf16 v[56:59], v[158:161], v[182:185], v[56:59]
	v_mfma_f32_16x16x32_bf16 v[44:47], v[144:147], v[190:193], v[44:47]
	v_mfma_f32_16x16x32_bf16 v[40:43], v[158:161], v[190:193], v[40:43]
	v_mfma_f32_16x16x32_bf16 v[28:31], v[144:147], v[198:201], v[28:31]
	v_mfma_f32_16x16x32_bf16 v[24:27], v[158:161], v[198:201], v[24:27]
	v_mfma_f32_16x16x32_bf16 v[12:15], v[144:147], v[206:209], v[12:15]
	v_mfma_f32_16x16x32_bf16 v[8:11], v[158:161], v[206:209], v[8:11]
	v_mfma_f32_16x16x32_bf16 v[60:63], v[154:157], v[186:189], v[60:63]
	v_mfma_f32_16x16x32_bf16 v[56:59], v[162:165], v[186:189], v[56:59]
	v_mfma_f32_16x16x32_bf16 v[44:47], v[154:157], v[194:197], v[44:47]
	v_mfma_f32_16x16x32_bf16 v[40:43], v[162:165], v[194:197], v[40:43]
	v_mfma_f32_16x16x32_bf16 v[28:31], v[154:157], v[202:205], v[28:31]
	v_mfma_f32_16x16x32_bf16 v[24:27], v[162:165], v[202:205], v[24:27]
	v_mfma_f32_16x16x32_bf16 v[12:15], v[154:157], v[210:213], v[12:15]
	v_mfma_f32_16x16x32_bf16 v[8:11], v[162:165], v[210:213], v[8:11]
	v_mfma_f32_16x16x32_bf16 v[52:55], v[166:169], v[182:185], v[52:55]
	v_mfma_f32_16x16x32_bf16 v[48:51], v[174:177], v[182:185], v[48:51]
	v_mfma_f32_16x16x32_bf16 v[36:39], v[166:169], v[190:193], v[36:39]
	v_mfma_f32_16x16x32_bf16 v[32:35], v[174:177], v[190:193], v[32:35]
	v_mfma_f32_16x16x32_bf16 v[20:23], v[166:169], v[198:201], v[20:23]
	v_mfma_f32_16x16x32_bf16 v[16:19], v[174:177], v[198:201], v[16:19]
	v_mfma_f32_16x16x32_bf16 v[4:7], v[166:169], v[206:209], v[4:7]
	v_mfma_f32_16x16x32_bf16 v[0:3], v[174:177], v[206:209], v[0:3]
	v_mfma_f32_16x16x32_bf16 v[52:55], v[170:173], v[186:189], v[52:55]
	v_mfma_f32_16x16x32_bf16 v[48:51], v[178:181], v[186:189], v[48:51]
	v_mfma_f32_16x16x32_bf16 v[36:39], v[170:173], v[194:197], v[36:39]
	v_mfma_f32_16x16x32_bf16 v[32:35], v[178:181], v[194:197], v[32:35]
	v_mfma_f32_16x16x32_bf16 v[20:23], v[170:173], v[202:205], v[20:23]
	v_mfma_f32_16x16x32_bf16 v[16:19], v[178:181], v[202:205], v[16:19]
	v_mfma_f32_16x16x32_bf16 v[4:7], v[170:173], v[210:213], v[4:7]
	v_mfma_f32_16x16x32_bf16 v[0:3], v[178:181], v[210:213], v[0:3]
	s_barrier
	s_add_i32 s37, 0, 0x18000
	s_add_i32 s40, 0, 0x1c000
	v_add_u32_e32 v162, s37, v149
	v_add_u32_e32 v178, s40, v149
	ds_read_b128 v[144:147], v162
	ds_read_b128 v[154:157], v162 offset:1024
	ds_read_b128 v[158:161], v162 offset:2048
	ds_read_b128 v[162:165], v162 offset:3072
	ds_read_b128 v[166:169], v178
	ds_read_b128 v[170:173], v178 offset:1024
	ds_read_b128 v[174:177], v178 offset:2048
	ds_read_b128 v[178:181], v178 offset:3072
	s_add_u32 s38, s54, 0x100000
	s_addc_u32 s39, s55, 0
	s_mov_b32 m0, s57
	ds_read_b128 v[182:185], v153 offset:32768
	ds_read_b128 v[186:189], v153 offset:33792
	ds_read_b128 v[190:193], v153 offset:34816
	ds_read_b128 v[194:197], v153 offset:35840
	ds_read_b128 v[198:201], v153 offset:36864
	ds_read_b128 v[202:205], v153 offset:37888
	ds_read_b128 v[206:209], v153 offset:38912
	ds_read_b128 v[210:213], v153 offset:39936
	global_load_lds_dwordx4 v128, s[38:39]
	s_mov_b32 m0, s58
	s_nop 0
	global_load_lds_dwordx4 v132, s[38:39]
	s_waitcnt vmcnt(8)
	s_waitcnt lgkmcnt(0)
	s_barrier
	s_waitcnt lgkmcnt(0)
	v_mfma_f32_16x16x32_bf16 v[124:127], v[144:147], v[182:185], v[124:127]
	v_mfma_f32_16x16x32_bf16 v[116:119], v[158:161], v[182:185], v[116:119]
	v_mfma_f32_16x16x32_bf16 v[108:111], v[144:147], v[190:193], v[108:111]
	v_mfma_f32_16x16x32_bf16 v[104:107], v[158:161], v[190:193], v[104:107]
	v_mfma_f32_16x16x32_bf16 v[92:95], v[144:147], v[198:201], v[92:95]
	v_mfma_f32_16x16x32_bf16 v[88:91], v[158:161], v[198:201], v[88:91]
	v_mfma_f32_16x16x32_bf16 v[76:79], v[144:147], v[206:209], v[76:79]
	v_mfma_f32_16x16x32_bf16 v[72:75], v[158:161], v[206:209], v[72:75]
	v_mfma_f32_16x16x32_bf16 v[124:127], v[154:157], v[186:189], v[124:127]
	v_mfma_f32_16x16x32_bf16 v[116:119], v[162:165], v[186:189], v[116:119]
	v_mfma_f32_16x16x32_bf16 v[108:111], v[154:157], v[194:197], v[108:111]
	v_mfma_f32_16x16x32_bf16 v[104:107], v[162:165], v[194:197], v[104:107]
	v_mfma_f32_16x16x32_bf16 v[92:95], v[154:157], v[202:205], v[92:95]
	v_mfma_f32_16x16x32_bf16 v[88:91], v[162:165], v[202:205], v[88:91]
	v_mfma_f32_16x16x32_bf16 v[76:79], v[154:157], v[210:213], v[76:79]
	v_mfma_f32_16x16x32_bf16 v[72:75], v[162:165], v[210:213], v[72:75]
	v_mfma_f32_16x16x32_bf16 v[120:123], v[166:169], v[182:185], v[120:123]
	v_mfma_f32_16x16x32_bf16 v[112:115], v[174:177], v[182:185], v[112:115]
	v_mfma_f32_16x16x32_bf16 v[100:103], v[166:169], v[190:193], v[100:103]
	v_mfma_f32_16x16x32_bf16 v[96:99], v[174:177], v[190:193], v[96:99]
	v_mfma_f32_16x16x32_bf16 v[84:87], v[166:169], v[198:201], v[84:87]
	v_mfma_f32_16x16x32_bf16 v[80:83], v[174:177], v[198:201], v[80:83]
	v_mfma_f32_16x16x32_bf16 v[68:71], v[166:169], v[206:209], v[68:71]
	v_mfma_f32_16x16x32_bf16 v[64:67], v[174:177], v[206:209], v[64:67]
	v_mfma_f32_16x16x32_bf16 v[120:123], v[170:173], v[186:189], v[120:123]
	v_mfma_f32_16x16x32_bf16 v[112:115], v[178:181], v[186:189], v[112:115]
	v_mfma_f32_16x16x32_bf16 v[100:103], v[170:173], v[194:197], v[100:103]
	v_mfma_f32_16x16x32_bf16 v[96:99], v[178:181], v[194:197], v[96:99]
	v_mfma_f32_16x16x32_bf16 v[84:87], v[170:173], v[202:205], v[84:87]
	v_mfma_f32_16x16x32_bf16 v[80:83], v[178:181], v[202:205], v[80:83]
	v_mfma_f32_16x16x32_bf16 v[68:71], v[170:173], v[210:213], v[68:71]
	v_mfma_f32_16x16x32_bf16 v[64:67], v[178:181], v[210:213], v[64:67]
	s_barrier
	s_add_i32 s37, s37, s33
	s_mov_b32 m0, s37
	ds_read_b128 v[182:185], v153 offset:49152
	ds_read_b128 v[186:189], v153 offset:50176
	ds_read_b128 v[190:193], v153 offset:51200
	ds_read_b128 v[194:197], v153 offset:52224
	ds_read_b128 v[198:201], v153 offset:53248
	ds_read_b128 v[202:205], v153 offset:54272
	ds_read_b128 v[206:209], v153 offset:55296
	ds_read_b128 v[210:213], v153 offset:56320
	s_add_u32 vcc_lo, s52, 0x80
	s_addc_u32 vcc_hi, s53, 0
	global_load_lds_dwordx4 v130, vcc
	s_add_i32 m0, s37, 0x2000
	s_add_u32 s38, s52, 0x100080
	s_addc_u32 s39, s53, 0
	s_add_i32 s37, s40, s33
	s_add_u32 vcc_lo, s52, 0x80
	s_addc_u32 vcc_hi, s53, 0
	global_load_lds_dwordx4 v134, vcc
	s_mov_b32 m0, s37
	s_nop 0
	global_load_lds_dwordx4 v130, s[38:39]
	s_add_i32 m0, s37, 0x2000
	s_nop 0
	global_load_lds_dwordx4 v134, s[38:39]
	s_mov_b32 m0, s60
	s_nop 0
	s_add_u32 vcc_lo, s54, 0x80
	s_addc_u32 vcc_hi, s55, 0
	global_load_lds_dwordx4 v128, vcc
	s_mov_b32 m0, s61
	s_nop 0
	s_add_u32 vcc_lo, s54, 0x80
	s_addc_u32 vcc_hi, s55, 0
	global_load_lds_dwordx4 v132, vcc
	s_waitcnt vmcnt(8)
	s_waitcnt lgkmcnt(0)
	s_barrier
	s_waitcnt lgkmcnt(0)
	v_mfma_f32_16x16x32_bf16 v[60:63], v[144:147], v[182:185], v[60:63]
	v_mfma_f32_16x16x32_bf16 v[56:59], v[158:161], v[182:185], v[56:59]
	v_mfma_f32_16x16x32_bf16 v[44:47], v[144:147], v[190:193], v[44:47]
	v_mfma_f32_16x16x32_bf16 v[40:43], v[158:161], v[190:193], v[40:43]
	v_mfma_f32_16x16x32_bf16 v[28:31], v[144:147], v[198:201], v[28:31]
	v_mfma_f32_16x16x32_bf16 v[24:27], v[158:161], v[198:201], v[24:27]
	v_mfma_f32_16x16x32_bf16 v[12:15], v[144:147], v[206:209], v[12:15]
	v_mfma_f32_16x16x32_bf16 v[8:11], v[158:161], v[206:209], v[8:11]
	v_mfma_f32_16x16x32_bf16 v[60:63], v[154:157], v[186:189], v[60:63]
	v_mfma_f32_16x16x32_bf16 v[56:59], v[162:165], v[186:189], v[56:59]
	v_mfma_f32_16x16x32_bf16 v[44:47], v[154:157], v[194:197], v[44:47]
	v_mfma_f32_16x16x32_bf16 v[40:43], v[162:165], v[194:197], v[40:43]
	v_mfma_f32_16x16x32_bf16 v[28:31], v[154:157], v[202:205], v[28:31]
	v_mfma_f32_16x16x32_bf16 v[24:27], v[162:165], v[202:205], v[24:27]
	v_mfma_f32_16x16x32_bf16 v[12:15], v[154:157], v[210:213], v[12:15]
	v_mfma_f32_16x16x32_bf16 v[8:11], v[162:165], v[210:213], v[8:11]
	v_mfma_f32_16x16x32_bf16 v[52:55], v[166:169], v[182:185], v[52:55]
	v_mfma_f32_16x16x32_bf16 v[48:51], v[174:177], v[182:185], v[48:51]
	v_mfma_f32_16x16x32_bf16 v[36:39], v[166:169], v[190:193], v[36:39]
	v_mfma_f32_16x16x32_bf16 v[32:35], v[174:177], v[190:193], v[32:35]
	v_mfma_f32_16x16x32_bf16 v[20:23], v[166:169], v[198:201], v[20:23]
	v_mfma_f32_16x16x32_bf16 v[16:19], v[174:177], v[198:201], v[16:19]
	v_mfma_f32_16x16x32_bf16 v[4:7], v[166:169], v[206:209], v[4:7]
	v_mfma_f32_16x16x32_bf16 v[0:3], v[174:177], v[206:209], v[0:3]
	v_mfma_f32_16x16x32_bf16 v[52:55], v[170:173], v[186:189], v[52:55]
	v_mfma_f32_16x16x32_bf16 v[48:51], v[178:181], v[186:189], v[48:51]
	v_mfma_f32_16x16x32_bf16 v[36:39], v[170:173], v[194:197], v[36:39]
	v_mfma_f32_16x16x32_bf16 v[32:35], v[178:181], v[194:197], v[32:35]
	v_mfma_f32_16x16x32_bf16 v[20:23], v[170:173], v[202:205], v[20:23]
	v_mfma_f32_16x16x32_bf16 v[16:19], v[178:181], v[202:205], v[16:19]
	v_mfma_f32_16x16x32_bf16 v[4:7], v[170:173], v[210:213], v[4:7]
	v_mfma_f32_16x16x32_bf16 v[0:3], v[178:181], v[210:213], v[0:3]
	s_barrier
	s_add_i32 s36, s36, 2
	s_add_u32 s50, s50, 0x100
	s_addc_u32 s51, s51, 0
	s_add_u32 s34, s34, 0x100
	s_addc_u32 s35, s35, 0
	s_cmp_gt_u32 s36, 61
	s_cbranch_scc0 .LBB0_679
	s_setprio 0
	s_and_b64 vcc, exec, s[12:13]
	s_cbranch_vccz .LBB0_682
	s_barrier

.Lmy_prio_skip4:
.LBB0_758:
	ds_read_b128 v[144:147], v153
	ds_read_b128 v[156:159], v153 offset:1024
	ds_read_b128 v[160:163], v153 offset:2048
	ds_read_b128 v[164:167], v153 offset:3072
	ds_read_b128 v[168:171], v154
	ds_read_b128 v[172:175], v154 offset:1024
	ds_read_b128 v[176:179], v154 offset:2048
	ds_read_b128 v[180:183], v154 offset:3072
	s_add_u32 s37, s38, 0xfff00080
	s_addc_u32 s40, s39, -1
	s_cmp_eq_u32 s36, 60
	s_cselect_b32 s49, s13, s40
	s_cselect_b32 s48, s64, s37
	s_cselect_b32 s47, s11, s35
	s_cselect_b32 s46, s65, s34
	s_add_i32 m0, s76, 0xc000
	ds_read_b128 v[184:187], v155
	ds_read_b128 v[188:191], v155 offset:1024
	ds_read_b128 v[192:195], v155 offset:2048
	ds_read_b128 v[196:199], v155 offset:3072
	ds_read_b128 v[200:203], v155 offset:4096
	ds_read_b128 v[204:207], v155 offset:5120
	ds_read_b128 v[208:211], v155 offset:6144
	ds_read_b128 v[212:215], v155 offset:7168
	global_load_lds_dwordx4 v136, s[38:39]
	s_add_i32 m0, s76, 0xe000
	s_nop 0
	global_load_lds_dwordx4 v138, s[38:39]
	s_waitcnt vmcnt(8)
	s_waitcnt lgkmcnt(0)
	s_barrier
	s_waitcnt lgkmcnt(0)
	v_mfma_f32_16x16x32_bf16 v[124:127], v[144:147], v[184:187], v[124:127]
	v_mfma_f32_16x16x32_bf16 v[120:123], v[160:163], v[184:187], v[120:123]
	v_mfma_f32_16x16x32_bf16 v[108:111], v[144:147], v[192:195], v[108:111]
	v_mfma_f32_16x16x32_bf16 v[104:107], v[160:163], v[192:195], v[104:107]
	v_mfma_f32_16x16x32_bf16 v[92:95], v[144:147], v[200:203], v[92:95]
	v_mfma_f32_16x16x32_bf16 v[88:91], v[160:163], v[200:203], v[88:91]
	v_mfma_f32_16x16x32_bf16 v[76:79], v[144:147], v[208:211], v[76:79]
	v_mfma_f32_16x16x32_bf16 v[72:75], v[160:163], v[208:211], v[72:75]
	v_mfma_f32_16x16x32_bf16 v[124:127], v[156:159], v[188:191], v[124:127]
	v_mfma_f32_16x16x32_bf16 v[120:123], v[164:167], v[188:191], v[120:123]
	v_mfma_f32_16x16x32_bf16 v[108:111], v[156:159], v[196:199], v[108:111]
	v_mfma_f32_16x16x32_bf16 v[104:107], v[164:167], v[196:199], v[104:107]
	v_mfma_f32_16x16x32_bf16 v[92:95], v[156:159], v[204:207], v[92:95]
	v_mfma_f32_16x16x32_bf16 v[88:91], v[164:167], v[204:207], v[88:91]
	v_mfma_f32_16x16x32_bf16 v[76:79], v[156:159], v[212:215], v[76:79]
	v_mfma_f32_16x16x32_bf16 v[72:75], v[164:167], v[212:215], v[72:75]
	v_mfma_f32_16x16x32_bf16 v[116:119], v[168:171], v[184:187], v[116:119]
	v_mfma_f32_16x16x32_bf16 v[112:115], v[176:179], v[184:187], v[112:115]
	v_mfma_f32_16x16x32_bf16 v[100:103], v[168:171], v[192:195], v[100:103]
	v_mfma_f32_16x16x32_bf16 v[96:99], v[176:179], v[192:195], v[96:99]
	v_mfma_f32_16x16x32_bf16 v[84:87], v[168:171], v[200:203], v[84:87]
	v_mfma_f32_16x16x32_bf16 v[80:83], v[176:179], v[200:203], v[80:83]
	v_mfma_f32_16x16x32_bf16 v[68:71], v[168:171], v[208:211], v[68:71]
	v_mfma_f32_16x16x32_bf16 v[64:67], v[176:179], v[208:211], v[64:67]
	v_mfma_f32_16x16x32_bf16 v[116:119], v[172:175], v[188:191], v[116:119]
	v_mfma_f32_16x16x32_bf16 v[112:115], v[180:183], v[188:191], v[112:115]
	v_mfma_f32_16x16x32_bf16 v[100:103], v[172:175], v[196:199], v[100:103]
	v_mfma_f32_16x16x32_bf16 v[96:99], v[180:183], v[196:199], v[96:99]
	v_mfma_f32_16x16x32_bf16 v[84:87], v[172:175], v[204:207], v[84:87]
	v_mfma_f32_16x16x32_bf16 v[80:83], v[180:183], v[204:207], v[80:83]
	v_mfma_f32_16x16x32_bf16 v[68:71], v[172:175], v[212:215], v[68:71]
	v_mfma_f32_16x16x32_bf16 v[64:67], v[180:183], v[212:215], v[64:67]
	s_barrier
	s_add_i32 s37, s61, s67
	s_mov_b32 m0, s37
	ds_read_b128 v[184:187], v155 offset:16384
	ds_read_b128 v[188:191], v155 offset:17408
	ds_read_b128 v[192:195], v155 offset:18432
	ds_read_b128 v[196:199], v155 offset:19456
	ds_read_b128 v[200:203], v155 offset:20480
	ds_read_b128 v[204:207], v155 offset:21504
	ds_read_b128 v[208:211], v155 offset:22528
	ds_read_b128 v[212:215], v155 offset:23552
	global_load_lds_dwordx4 v130, s[46:47]
	s_add_i32 m0, s37, 0x2000
	s_add_u32 s40, s46, 0x100000
	s_addc_u32 s41, s47, 0
	s_add_i32 s37, s62, s67
	global_load_lds_dwordx4 v134, s[46:47]
	s_mov_b32 m0, s37
	global_load_lds_dwordx4 v130, s[40:41]
	s_add_i32 m0, s37, 0x2000
	s_nop 0
	global_load_lds_dwordx4 v134, s[40:41]
	s_mov_b32 m0, s76
	s_nop 0
	global_load_lds_dwordx4 v128, s[48:49]
	s_mov_b32 m0, s52
	s_nop 0
	global_load_lds_dwordx4 v132, s[48:49]
	s_waitcnt vmcnt(8)
	s_waitcnt lgkmcnt(0)
	s_barrier
	s_waitcnt lgkmcnt(0)
	v_mfma_f32_16x16x32_bf16 v[60:63], v[144:147], v[184:187], v[60:63]
	v_mfma_f32_16x16x32_bf16 v[56:59], v[160:163], v[184:187], v[56:59]
	v_mfma_f32_16x16x32_bf16 v[44:47], v[144:147], v[192:195], v[44:47]
	v_mfma_f32_16x16x32_bf16 v[40:43], v[160:163], v[192:195], v[40:43]
	v_mfma_f32_16x16x32_bf16 v[28:31], v[144:147], v[200:203], v[28:31]
	v_mfma_f32_16x16x32_bf16 v[24:27], v[160:163], v[200:203], v[24:27]
	v_mfma_f32_16x16x32_bf16 v[12:15], v[144:147], v[208:211], v[12:15]
	v_mfma_f32_16x16x32_bf16 v[8:11], v[160:163], v[208:211], v[8:11]
	v_mfma_f32_16x16x32_bf16 v[60:63], v[156:159], v[188:191], v[60:63]
	v_mfma_f32_16x16x32_bf16 v[56:59], v[164:167], v[188:191], v[56:59]
	v_mfma_f32_16x16x32_bf16 v[44:47], v[156:159], v[196:199], v[44:47]
	v_mfma_f32_16x16x32_bf16 v[40:43], v[164:167], v[196:199], v[40:43]
	v_mfma_f32_16x16x32_bf16 v[28:31], v[156:159], v[204:207], v[28:31]
	v_mfma_f32_16x16x32_bf16 v[24:27], v[164:167], v[204:207], v[24:27]
	v_mfma_f32_16x16x32_bf16 v[12:15], v[156:159], v[212:215], v[12:15]
	v_mfma_f32_16x16x32_bf16 v[8:11], v[164:167], v[212:215], v[8:11]
	v_mfma_f32_16x16x32_bf16 v[52:55], v[168:171], v[184:187], v[52:55]
	v_mfma_f32_16x16x32_bf16 v[48:51], v[176:179], v[184:187], v[48:51]
	v_mfma_f32_16x16x32_bf16 v[36:39], v[168:171], v[192:195], v[36:39]
	v_mfma_f32_16x16x32_bf16 v[32:35], v[176:179], v[192:195], v[32:35]
	v_mfma_f32_16x16x32_bf16 v[20:23], v[168:171], v[200:203], v[20:23]
	v_mfma_f32_16x16x32_bf16 v[16:19], v[176:179], v[200:203], v[16:19]
	v_mfma_f32_16x16x32_bf16 v[4:7], v[168:171], v[208:211], v[4:7]
	v_mfma_f32_16x16x32_bf16 v[0:3], v[176:179], v[208:211], v[0:3]
	v_mfma_f32_16x16x32_bf16 v[52:55], v[172:175], v[188:191], v[52:55]
	v_mfma_f32_16x16x32_bf16 v[48:51], v[180:183], v[188:191], v[48:51]
	v_mfma_f32_16x16x32_bf16 v[36:39], v[172:175], v[196:199], v[36:39]
	v_mfma_f32_16x16x32_bf16 v[32:35], v[180:183], v[196:199], v[32:35]
	v_mfma_f32_16x16x32_bf16 v[20:23], v[172:175], v[204:207], v[20:23]
	v_mfma_f32_16x16x32_bf16 v[16:19], v[180:183], v[204:207], v[16:19]
	v_mfma_f32_16x16x32_bf16 v[4:7], v[172:175], v[212:215], v[4:7]
	v_mfma_f32_16x16x32_bf16 v[0:3], v[180:183], v[212:215], v[0:3]
	s_barrier
	s_add_i32 s37, 0, 0x18000
	s_add_i32 s42, 0, 0x1c000
	v_add_u32_e32 v164, s37, v151
	v_add_u32_e32 v180, s42, v151
	ds_read_b128 v[144:147], v164
	ds_read_b128 v[156:159], v164 offset:1024
	ds_read_b128 v[160:163], v164 offset:2048
	ds_read_b128 v[164:167], v164 offset:3072
	ds_read_b128 v[168:171], v180
	ds_read_b128 v[172:175], v180 offset:1024
	ds_read_b128 v[176:179], v180 offset:2048
	ds_read_b128 v[180:183], v180 offset:3072
	s_add_u32 s40, s48, 0x100000
	s_addc_u32 s41, s49, 0
	s_mov_b32 m0, s53
	ds_read_b128 v[184:187], v155 offset:32768
	ds_read_b128 v[188:191], v155 offset:33792
	ds_read_b128 v[192:195], v155 offset:34816
	ds_read_b128 v[196:199], v155 offset:35840
	ds_read_b128 v[200:203], v155 offset:36864
	ds_read_b128 v[204:207], v155 offset:37888
	ds_read_b128 v[208:211], v155 offset:38912
	ds_read_b128 v[212:215], v155 offset:39936
	global_load_lds_dwordx4 v128, s[40:41]
	s_mov_b32 m0, s54
	s_nop 0
	global_load_lds_dwordx4 v132, s[40:41]
	s_waitcnt vmcnt(8)
	s_waitcnt lgkmcnt(0)
	s_barrier
	s_waitcnt lgkmcnt(0)
	v_mfma_f32_16x16x32_bf16 v[124:127], v[144:147], v[184:187], v[124:127]
	v_mfma_f32_16x16x32_bf16 v[120:123], v[160:163], v[184:187], v[120:123]
	v_mfma_f32_16x16x32_bf16 v[108:111], v[144:147], v[192:195], v[108:111]
	v_mfma_f32_16x16x32_bf16 v[104:107], v[160:163], v[192:195], v[104:107]
	v_mfma_f32_16x16x32_bf16 v[92:95], v[144:147], v[200:203], v[92:95]
	v_mfma_f32_16x16x32_bf16 v[88:91], v[160:163], v[200:203], v[88:91]
	v_mfma_f32_16x16x32_bf16 v[76:79], v[144:147], v[208:211], v[76:79]
	v_mfma_f32_16x16x32_bf16 v[72:75], v[160:163], v[208:211], v[72:75]
	v_mfma_f32_16x16x32_bf16 v[124:127], v[156:159], v[188:191], v[124:127]
	v_mfma_f32_16x16x32_bf16 v[120:123], v[164:167], v[188:191], v[120:123]
	v_mfma_f32_16x16x32_bf16 v[108:111], v[156:159], v[196:199], v[108:111]
	v_mfma_f32_16x16x32_bf16 v[104:107], v[164:167], v[196:199], v[104:107]
	v_mfma_f32_16x16x32_bf16 v[92:95], v[156:159], v[204:207], v[92:95]
	v_mfma_f32_16x16x32_bf16 v[88:91], v[164:167], v[204:207], v[88:91]
	v_mfma_f32_16x16x32_bf16 v[76:79], v[156:159], v[212:215], v[76:79]
	v_mfma_f32_16x16x32_bf16 v[72:75], v[164:167], v[212:215], v[72:75]
	v_mfma_f32_16x16x32_bf16 v[116:119], v[168:171], v[184:187], v[116:119]
	v_mfma_f32_16x16x32_bf16 v[112:115], v[176:179], v[184:187], v[112:115]
	v_mfma_f32_16x16x32_bf16 v[100:103], v[168:171], v[192:195], v[100:103]
	v_mfma_f32_16x16x32_bf16 v[96:99], v[176:179], v[192:195], v[96:99]
	v_mfma_f32_16x16x32_bf16 v[84:87], v[168:171], v[200:203], v[84:87]
	v_mfma_f32_16x16x32_bf16 v[80:83], v[176:179], v[200:203], v[80:83]
	v_mfma_f32_16x16x32_bf16 v[68:71], v[168:171], v[208:211], v[68:71]
	v_mfma_f32_16x16x32_bf16 v[64:67], v[176:179], v[208:211], v[64:67]
	v_mfma_f32_16x16x32_bf16 v[116:119], v[172:175], v[188:191], v[116:119]
	v_mfma_f32_16x16x32_bf16 v[112:115], v[180:183], v[188:191], v[112:115]
	v_mfma_f32_16x16x32_bf16 v[100:103], v[172:175], v[196:199], v[100:103]
	v_mfma_f32_16x16x32_bf16 v[96:99], v[180:183], v[196:199], v[96:99]
	v_mfma_f32_16x16x32_bf16 v[84:87], v[172:175], v[204:207], v[84:87]
	v_mfma_f32_16x16x32_bf16 v[80:83], v[180:183], v[204:207], v[80:83]
	v_mfma_f32_16x16x32_bf16 v[68:71], v[172:175], v[212:215], v[68:71]
	v_mfma_f32_16x16x32_bf16 v[64:67], v[180:183], v[212:215], v[64:67]
	s_barrier
	s_add_i32 s37, s37, s67
	s_mov_b32 m0, s37
	ds_read_b128 v[184:187], v155 offset:49152
	ds_read_b128 v[188:191], v155 offset:50176
	ds_read_b128 v[192:195], v155 offset:51200
	ds_read_b128 v[196:199], v155 offset:52224
	ds_read_b128 v[200:203], v155 offset:53248
	ds_read_b128 v[204:207], v155 offset:54272
	ds_read_b128 v[208:211], v155 offset:55296
	ds_read_b128 v[212:215], v155 offset:56320
	s_add_u32 vcc_lo, s46, 0x80
	s_addc_u32 vcc_hi, s47, 0
	global_load_lds_dwordx4 v130, vcc
	s_add_i32 m0, s37, 0x2000
	s_add_u32 s40, s46, 0x100080
	s_addc_u32 s41, s47, 0
	s_add_i32 s37, s42, s67
	s_add_u32 vcc_lo, s46, 0x80
	s_addc_u32 vcc_hi, s47, 0
	global_load_lds_dwordx4 v134, vcc
	s_mov_b32 m0, s37
	s_nop 0
	global_load_lds_dwordx4 v130, s[40:41]
	s_add_i32 m0, s37, 0x2000
	s_nop 0
	global_load_lds_dwordx4 v134, s[40:41]
	s_mov_b32 m0, s56
	s_nop 0
	s_add_u32 vcc_lo, s48, 0x80
	s_addc_u32 vcc_hi, s49, 0
	global_load_lds_dwordx4 v128, vcc
	s_mov_b32 m0, s57
	s_nop 0
	s_add_u32 vcc_lo, s48, 0x80
	s_addc_u32 vcc_hi, s49, 0
	global_load_lds_dwordx4 v132, vcc
	s_waitcnt vmcnt(8)
	s_waitcnt lgkmcnt(0)
	s_barrier
	s_waitcnt lgkmcnt(0)
	v_mfma_f32_16x16x32_bf16 v[60:63], v[144:147], v[184:187], v[60:63]
	v_mfma_f32_16x16x32_bf16 v[56:59], v[160:163], v[184:187], v[56:59]
	v_mfma_f32_16x16x32_bf16 v[44:47], v[144:147], v[192:195], v[44:47]
	v_mfma_f32_16x16x32_bf16 v[40:43], v[160:163], v[192:195], v[40:43]
	v_mfma_f32_16x16x32_bf16 v[28:31], v[144:147], v[200:203], v[28:31]
	v_mfma_f32_16x16x32_bf16 v[24:27], v[160:163], v[200:203], v[24:27]
	v_mfma_f32_16x16x32_bf16 v[12:15], v[144:147], v[208:211], v[12:15]
	v_mfma_f32_16x16x32_bf16 v[8:11], v[160:163], v[208:211], v[8:11]
	v_mfma_f32_16x16x32_bf16 v[60:63], v[156:159], v[188:191], v[60:63]
	v_mfma_f32_16x16x32_bf16 v[56:59], v[164:167], v[188:191], v[56:59]
	v_mfma_f32_16x16x32_bf16 v[44:47], v[156:159], v[196:199], v[44:47]
	v_mfma_f32_16x16x32_bf16 v[40:43], v[164:167], v[196:199], v[40:43]
	v_mfma_f32_16x16x32_bf16 v[28:31], v[156:159], v[204:207], v[28:31]
	v_mfma_f32_16x16x32_bf16 v[24:27], v[164:167], v[204:207], v[24:27]
	v_mfma_f32_16x16x32_bf16 v[12:15], v[156:159], v[212:215], v[12:15]
	v_mfma_f32_16x16x32_bf16 v[8:11], v[164:167], v[212:215], v[8:11]
	v_mfma_f32_16x16x32_bf16 v[52:55], v[168:171], v[184:187], v[52:55]
	v_mfma_f32_16x16x32_bf16 v[48:51], v[176:179], v[184:187], v[48:51]
	v_mfma_f32_16x16x32_bf16 v[36:39], v[168:171], v[192:195], v[36:39]
	v_mfma_f32_16x16x32_bf16 v[32:35], v[176:179], v[192:195], v[32:35]
	v_mfma_f32_16x16x32_bf16 v[20:23], v[168:171], v[200:203], v[20:23]
	v_mfma_f32_16x16x32_bf16 v[16:19], v[176:179], v[200:203], v[16:19]
	v_mfma_f32_16x16x32_bf16 v[4:7], v[168:171], v[208:211], v[4:7]
	v_mfma_f32_16x16x32_bf16 v[0:3], v[176:179], v[208:211], v[0:3]
	v_mfma_f32_16x16x32_bf16 v[52:55], v[172:175], v[188:191], v[52:55]
	v_mfma_f32_16x16x32_bf16 v[48:51], v[180:183], v[188:191], v[48:51]
	v_mfma_f32_16x16x32_bf16 v[36:39], v[172:175], v[196:199], v[36:39]
	v_mfma_f32_16x16x32_bf16 v[32:35], v[180:183], v[196:199], v[32:35]
	v_mfma_f32_16x16x32_bf16 v[20:23], v[172:175], v[204:207], v[20:23]
	v_mfma_f32_16x16x32_bf16 v[16:19], v[180:183], v[204:207], v[16:19]
	v_mfma_f32_16x16x32_bf16 v[4:7], v[172:175], v[212:215], v[4:7]
	v_mfma_f32_16x16x32_bf16 v[0:3], v[180:183], v[212:215], v[0:3]
	s_barrier
	s_add_i32 s36, s36, 2
	s_add_u32 s38, s38, 0x100
	s_addc_u32 s39, s39, 0
	s_add_u32 s34, s34, 0x100
	s_addc_u32 s35, s35, 0
	s_cmp_gt_u32 s36, 61
	s_cbranch_scc0 .LBB0_758
	s_setprio 0
	s_and_b64 vcc, exec, s[8:9]
	s_cbranch_vccz .LBB0_761
	s_barrier

.Lmy_prio_skip5:
.LBB0_914:
	ds_read_b128 v[128:131], v187
	ds_read_b128 v[132:135], v187 offset:1024
	ds_read_b128 v[136:139], v187 offset:2048
	ds_read_b128 v[140:143], v187 offset:3072
	ds_read_b128 v[144:147], v188
	ds_read_b128 v[148:151], v188 offset:1024
	ds_read_b128 v[152:155], v188 offset:2048
	ds_read_b128 v[156:159], v188 offset:3072
	s_add_u32 s52, s50, 0x100
	s_addc_u32 s53, s51, 0
	s_cmp_eq_u32 s96, 60
	s_cselect_b32 s57, s41, s53
	s_cselect_b32 s56, s47, s52
	s_cselect_b32 s55, s39, s49
	s_cselect_b32 s54, s34, s35
	s_add_i32 m0, s67, 0xc000
	ds_read_b128 v[178:181], v189
	ds_read_b128 v[192:195], v189 offset:1024
	ds_read_b128 v[196:199], v189 offset:2048
	ds_read_b128 v[200:203], v189 offset:3072
	ds_read_b128 v[204:207], v189 offset:4096
	ds_read_b128 v[208:211], v189 offset:5120
	ds_read_b128 v[212:215], v189 offset:6144
	ds_read_b128 v[216:219], v189 offset:7168
	global_load_lds_dwordx4 v170, s[50:51]
	s_add_i32 m0, s67, 0xe000
	s_nop 0
	global_load_lds_dwordx4 v172, s[50:51]
	s_waitcnt vmcnt(8)
	s_waitcnt lgkmcnt(0)
	s_barrier
	s_waitcnt lgkmcnt(0)
	v_mfma_f32_16x16x32_bf16 v[124:127], v[128:131], v[178:181], v[124:127]
	v_mfma_f32_16x16x32_bf16 v[60:63], v[136:139], v[178:181], v[60:63]
	v_mfma_f32_16x16x32_bf16 v[116:119], v[128:131], v[196:199], v[116:119]
	v_mfma_f32_16x16x32_bf16 v[56:59], v[136:139], v[196:199], v[56:59]
	v_mfma_f32_16x16x32_bf16 v[108:111], v[128:131], v[204:207], v[108:111]
	v_mfma_f32_16x16x32_bf16 v[44:47], v[136:139], v[204:207], v[44:47]
	v_mfma_f32_16x16x32_bf16 v[104:107], v[128:131], v[212:215], v[104:107]
	v_mfma_f32_16x16x32_bf16 v[40:43], v[136:139], v[212:215], v[40:43]
	v_mfma_f32_16x16x32_bf16 v[124:127], v[132:135], v[192:195], v[124:127]
	v_mfma_f32_16x16x32_bf16 v[60:63], v[140:143], v[192:195], v[60:63]
	v_mfma_f32_16x16x32_bf16 v[116:119], v[132:135], v[200:203], v[116:119]
	v_mfma_f32_16x16x32_bf16 v[56:59], v[140:143], v[200:203], v[56:59]
	v_mfma_f32_16x16x32_bf16 v[108:111], v[132:135], v[208:211], v[108:111]
	v_mfma_f32_16x16x32_bf16 v[44:47], v[140:143], v[208:211], v[44:47]
	v_mfma_f32_16x16x32_bf16 v[104:107], v[132:135], v[216:219], v[104:107]
	v_mfma_f32_16x16x32_bf16 v[40:43], v[140:143], v[216:219], v[40:43]
	v_mfma_f32_16x16x32_bf16 v[120:123], v[144:147], v[178:181], v[120:123]
	v_mfma_f32_16x16x32_bf16 v[52:55], v[152:155], v[178:181], v[52:55]
	v_mfma_f32_16x16x32_bf16 v[112:115], v[144:147], v[196:199], v[112:115]
	v_mfma_f32_16x16x32_bf16 v[48:51], v[152:155], v[196:199], v[48:51]
	v_mfma_f32_16x16x32_bf16 v[100:103], v[144:147], v[204:207], v[100:103]
	v_mfma_f32_16x16x32_bf16 v[36:39], v[152:155], v[204:207], v[36:39]
	v_mfma_f32_16x16x32_bf16 v[96:99], v[144:147], v[212:215], v[96:99]
	v_mfma_f32_16x16x32_bf16 v[32:35], v[152:155], v[212:215], v[32:35]
	v_mfma_f32_16x16x32_bf16 v[120:123], v[148:151], v[192:195], v[120:123]
	v_mfma_f32_16x16x32_bf16 v[52:55], v[156:159], v[192:195], v[52:55]
	v_mfma_f32_16x16x32_bf16 v[112:115], v[148:151], v[200:203], v[112:115]
	v_mfma_f32_16x16x32_bf16 v[48:51], v[156:159], v[200:203], v[48:51]
	v_mfma_f32_16x16x32_bf16 v[100:103], v[148:151], v[208:211], v[100:103]
	v_mfma_f32_16x16x32_bf16 v[36:39], v[156:159], v[208:211], v[36:39]
	v_mfma_f32_16x16x32_bf16 v[96:99], v[148:151], v[216:219], v[96:99]
	v_mfma_f32_16x16x32_bf16 v[32:35], v[156:159], v[216:219], v[32:35]
	s_barrier
	s_add_i32 s50, s92, s66
	v_lshl_add_u64 v[160:161], s[54:55], 0, v[164:165]
	s_mov_b32 m0, s50
	ds_read_b128 v[178:181], v189 offset:16384
	ds_read_b128 v[192:195], v189 offset:17408
	ds_read_b128 v[196:199], v189 offset:18432
	ds_read_b128 v[200:203], v189 offset:19456
	ds_read_b128 v[204:207], v189 offset:20480
	ds_read_b128 v[208:211], v189 offset:21504
	ds_read_b128 v[212:215], v189 offset:22528
	ds_read_b128 v[216:219], v189 offset:23552
	global_load_lds_dwordx4 v164, s[54:55]
	s_add_i32 m0, s50, 0x2000
	s_add_u32 s50, s54, 0x100000
	v_lshl_add_u64 v[182:183], s[54:55], 0, v[168:169]
	s_addc_u32 s51, s55, 0
	s_add_i32 s97, s93, s66
	global_load_lds_dwordx4 v168, s[54:55]
	s_mov_b32 m0, s97
	v_lshl_add_u64 v[222:223], s[56:57], 0, v[166:167]
	global_load_lds_dwordx4 v164, s[50:51]
	s_add_i32 m0, s97, 0x2000
	s_nop 0
	global_load_lds_dwordx4 v168, s[50:51]
	v_lshl_add_u64 v[220:221], s[56:57], 0, v[162:163]
	s_mov_b32 m0, s67
	s_nop 0
	global_load_lds_dwordx4 v162, s[56:57]
	s_mov_b32 m0, s68
	s_nop 0
	global_load_lds_dwordx4 v166, s[56:57]
	s_waitcnt vmcnt(8)
	s_waitcnt lgkmcnt(0)
	s_barrier
	s_waitcnt lgkmcnt(0)
	v_mfma_f32_16x16x32_bf16 v[92:95], v[128:131], v[178:181], v[92:95]
	v_mfma_f32_16x16x32_bf16 v[28:31], v[136:139], v[178:181], v[28:31]
	v_mfma_f32_16x16x32_bf16 v[84:87], v[128:131], v[196:199], v[84:87]
	v_mfma_f32_16x16x32_bf16 v[24:27], v[136:139], v[196:199], v[24:27]
	v_mfma_f32_16x16x32_bf16 v[76:79], v[128:131], v[204:207], v[76:79]
	v_mfma_f32_16x16x32_bf16 v[12:15], v[136:139], v[204:207], v[12:15]
	v_mfma_f32_16x16x32_bf16 v[72:75], v[128:131], v[212:215], v[72:75]
	v_mfma_f32_16x16x32_bf16 v[8:11], v[136:139], v[212:215], v[8:11]
	v_mfma_f32_16x16x32_bf16 v[92:95], v[132:135], v[192:195], v[92:95]
	v_mfma_f32_16x16x32_bf16 v[28:31], v[140:143], v[192:195], v[28:31]
	v_mfma_f32_16x16x32_bf16 v[84:87], v[132:135], v[200:203], v[84:87]
	v_mfma_f32_16x16x32_bf16 v[24:27], v[140:143], v[200:203], v[24:27]
	v_mfma_f32_16x16x32_bf16 v[76:79], v[132:135], v[208:211], v[76:79]
	v_mfma_f32_16x16x32_bf16 v[12:15], v[140:143], v[208:211], v[12:15]
	v_mfma_f32_16x16x32_bf16 v[72:75], v[132:135], v[216:219], v[72:75]
	v_mfma_f32_16x16x32_bf16 v[8:11], v[140:143], v[216:219], v[8:11]
	v_mfma_f32_16x16x32_bf16 v[88:91], v[144:147], v[178:181], v[88:91]
	v_mfma_f32_16x16x32_bf16 v[20:23], v[152:155], v[178:181], v[20:23]
	v_mfma_f32_16x16x32_bf16 v[80:83], v[144:147], v[196:199], v[80:83]
	v_mfma_f32_16x16x32_bf16 v[16:19], v[152:155], v[196:199], v[16:19]
	v_mfma_f32_16x16x32_bf16 v[68:71], v[144:147], v[204:207], v[68:71]
	v_mfma_f32_16x16x32_bf16 v[4:7], v[152:155], v[204:207], v[4:7]
	v_mfma_f32_16x16x32_bf16 v[64:67], v[144:147], v[212:215], v[64:67]
	v_mfma_f32_16x16x32_bf16 v[0:3], v[152:155], v[212:215], v[0:3]
	v_mfma_f32_16x16x32_bf16 v[88:91], v[148:151], v[192:195], v[88:91]
	v_mfma_f32_16x16x32_bf16 v[20:23], v[156:159], v[192:195], v[20:23]
	v_mfma_f32_16x16x32_bf16 v[80:83], v[148:151], v[200:203], v[80:83]
	v_mfma_f32_16x16x32_bf16 v[16:19], v[156:159], v[200:203], v[16:19]
	v_mfma_f32_16x16x32_bf16 v[68:71], v[148:151], v[208:211], v[68:71]
	v_mfma_f32_16x16x32_bf16 v[4:7], v[156:159], v[208:211], v[4:7]
	v_mfma_f32_16x16x32_bf16 v[64:67], v[148:151], v[216:219], v[64:67]
	v_mfma_f32_16x16x32_bf16 v[0:3], v[156:159], v[216:219], v[0:3]
	s_barrier
	s_add_i32 s97, 0, 0x18000
	s_add_i32 vcc_lo, 0, 0x1c000
	v_add_u32_e32 v140, s97, v184
	v_add_u32_e32 v156, vcc_lo, v184
	ds_read_b128 v[128:131], v140
	ds_read_b128 v[132:135], v140 offset:1024
	ds_read_b128 v[136:139], v140 offset:2048
	ds_read_b128 v[140:143], v140 offset:3072
	ds_read_b128 v[144:147], v156
	ds_read_b128 v[148:151], v156 offset:1024
	ds_read_b128 v[152:155], v156 offset:2048
	ds_read_b128 v[156:159], v156 offset:3072
	s_add_u32 s50, s56, 0x100000
	s_addc_u32 s51, s57, 0
	s_mov_b32 m0, s69
	ds_read_b128 v[178:181], v189 offset:32768
	ds_read_b128 v[192:195], v189 offset:33792
	ds_read_b128 v[196:199], v189 offset:34816
	ds_read_b128 v[200:203], v189 offset:35840
	ds_read_b128 v[204:207], v189 offset:36864
	ds_read_b128 v[208:211], v189 offset:37888
	ds_read_b128 v[212:215], v189 offset:38912
	ds_read_b128 v[216:219], v189 offset:39936
	global_load_lds_dwordx4 v162, s[50:51]
	s_mov_b32 m0, s76
	s_nop 0
	global_load_lds_dwordx4 v166, s[50:51]
	s_waitcnt vmcnt(8)
	s_waitcnt lgkmcnt(0)
	s_barrier
	s_waitcnt lgkmcnt(0)
	v_mfma_f32_16x16x32_bf16 v[124:127], v[128:131], v[178:181], v[124:127]
	v_mfma_f32_16x16x32_bf16 v[60:63], v[136:139], v[178:181], v[60:63]
	v_mfma_f32_16x16x32_bf16 v[116:119], v[128:131], v[196:199], v[116:119]
	v_mfma_f32_16x16x32_bf16 v[56:59], v[136:139], v[196:199], v[56:59]
	v_mfma_f32_16x16x32_bf16 v[108:111], v[128:131], v[204:207], v[108:111]
	v_mfma_f32_16x16x32_bf16 v[44:47], v[136:139], v[204:207], v[44:47]
	v_mfma_f32_16x16x32_bf16 v[104:107], v[128:131], v[212:215], v[104:107]
	v_mfma_f32_16x16x32_bf16 v[40:43], v[136:139], v[212:215], v[40:43]
	v_mfma_f32_16x16x32_bf16 v[124:127], v[132:135], v[192:195], v[124:127]
	v_mfma_f32_16x16x32_bf16 v[60:63], v[140:143], v[192:195], v[60:63]
	v_mfma_f32_16x16x32_bf16 v[116:119], v[132:135], v[200:203], v[116:119]
	v_mfma_f32_16x16x32_bf16 v[56:59], v[140:143], v[200:203], v[56:59]
	v_mfma_f32_16x16x32_bf16 v[108:111], v[132:135], v[208:211], v[108:111]
	v_mfma_f32_16x16x32_bf16 v[44:47], v[140:143], v[208:211], v[44:47]
	v_mfma_f32_16x16x32_bf16 v[104:107], v[132:135], v[216:219], v[104:107]
	v_mfma_f32_16x16x32_bf16 v[40:43], v[140:143], v[216:219], v[40:43]
	v_mfma_f32_16x16x32_bf16 v[120:123], v[144:147], v[178:181], v[120:123]
	v_mfma_f32_16x16x32_bf16 v[52:55], v[152:155], v[178:181], v[52:55]
	v_mfma_f32_16x16x32_bf16 v[112:115], v[144:147], v[196:199], v[112:115]
	v_mfma_f32_16x16x32_bf16 v[48:51], v[152:155], v[196:199], v[48:51]
	v_mfma_f32_16x16x32_bf16 v[100:103], v[144:147], v[204:207], v[100:103]
	v_mfma_f32_16x16x32_bf16 v[36:39], v[152:155], v[204:207], v[36:39]
	v_mfma_f32_16x16x32_bf16 v[96:99], v[144:147], v[212:215], v[96:99]
	v_mfma_f32_16x16x32_bf16 v[32:35], v[152:155], v[212:215], v[32:35]
	v_mfma_f32_16x16x32_bf16 v[120:123], v[148:151], v[192:195], v[120:123]
	v_mfma_f32_16x16x32_bf16 v[52:55], v[156:159], v[192:195], v[52:55]
	v_mfma_f32_16x16x32_bf16 v[112:115], v[148:151], v[200:203], v[112:115]
	v_mfma_f32_16x16x32_bf16 v[48:51], v[156:159], v[200:203], v[48:51]
	v_mfma_f32_16x16x32_bf16 v[100:103], v[148:151], v[208:211], v[100:103]
	v_mfma_f32_16x16x32_bf16 v[36:39], v[156:159], v[208:211], v[36:39]
	v_mfma_f32_16x16x32_bf16 v[96:99], v[148:151], v[216:219], v[96:99]
	v_mfma_f32_16x16x32_bf16 v[32:35], v[156:159], v[216:219], v[32:35]
	s_barrier
	s_add_i32 s50, s97, s66
	v_lshl_add_u64 v[160:161], v[160:161], 0, s[10:11]
	s_mov_b32 m0, s50
	ds_read_b128 v[178:181], v189 offset:49152
	ds_read_b128 v[192:195], v189 offset:50176
	ds_read_b128 v[196:199], v189 offset:51200
	ds_read_b128 v[200:203], v189 offset:52224
	ds_read_b128 v[204:207], v189 offset:53248
	ds_read_b128 v[208:211], v189 offset:54272
	ds_read_b128 v[212:215], v189 offset:55296
	ds_read_b128 v[216:219], v189 offset:56320
	global_load_lds_dwordx4 v[160:161], off
	s_add_i32 m0, s50, 0x2000
	s_add_u32 s50, s54, 0x100080
	v_lshl_add_u64 v[160:161], v[182:183], 0, s[10:11]
	s_addc_u32 s51, s55, 0
	s_add_i32 s54, vcc_lo, s66
	global_load_lds_dwordx4 v[160:161], off
	s_mov_b32 m0, s54
	s_nop 0
	global_load_lds_dwordx4 v164, s[50:51]
	s_add_i32 m0, s54, 0x2000
	s_nop 0
	global_load_lds_dwordx4 v168, s[50:51]
	v_lshl_add_u64 v[160:161], v[220:221], 0, s[10:11]
	s_mov_b32 m0, s84
	s_nop 0
	global_load_lds_dwordx4 v[160:161], off
	v_lshl_add_u64 v[160:161], v[222:223], 0, s[10:11]
	s_mov_b32 m0, s85
	s_nop 0
	global_load_lds_dwordx4 v[160:161], off
	s_waitcnt vmcnt(8)
	s_waitcnt lgkmcnt(0)
	s_barrier
	s_waitcnt lgkmcnt(0)
	v_mfma_f32_16x16x32_bf16 v[92:95], v[128:131], v[178:181], v[92:95]
	v_mfma_f32_16x16x32_bf16 v[28:31], v[136:139], v[178:181], v[28:31]
	v_mfma_f32_16x16x32_bf16 v[84:87], v[128:131], v[196:199], v[84:87]
	v_mfma_f32_16x16x32_bf16 v[24:27], v[136:139], v[196:199], v[24:27]
	v_mfma_f32_16x16x32_bf16 v[76:79], v[128:131], v[204:207], v[76:79]
	v_mfma_f32_16x16x32_bf16 v[12:15], v[136:139], v[204:207], v[12:15]
	v_mfma_f32_16x16x32_bf16 v[72:75], v[128:131], v[212:215], v[72:75]
	v_mfma_f32_16x16x32_bf16 v[8:11], v[136:139], v[212:215], v[8:11]
	v_mfma_f32_16x16x32_bf16 v[92:95], v[132:135], v[192:195], v[92:95]
	v_mfma_f32_16x16x32_bf16 v[28:31], v[140:143], v[192:195], v[28:31]
	v_mfma_f32_16x16x32_bf16 v[84:87], v[132:135], v[200:203], v[84:87]
	v_mfma_f32_16x16x32_bf16 v[24:27], v[140:143], v[200:203], v[24:27]
	v_mfma_f32_16x16x32_bf16 v[76:79], v[132:135], v[208:211], v[76:79]
	v_mfma_f32_16x16x32_bf16 v[12:15], v[140:143], v[208:211], v[12:15]
	v_mfma_f32_16x16x32_bf16 v[72:75], v[132:135], v[216:219], v[72:75]
	v_mfma_f32_16x16x32_bf16 v[8:11], v[140:143], v[216:219], v[8:11]
	v_mfma_f32_16x16x32_bf16 v[88:91], v[144:147], v[178:181], v[88:91]
	v_mfma_f32_16x16x32_bf16 v[20:23], v[152:155], v[178:181], v[20:23]
	v_mfma_f32_16x16x32_bf16 v[80:83], v[144:147], v[196:199], v[80:83]
	v_mfma_f32_16x16x32_bf16 v[16:19], v[152:155], v[196:199], v[16:19]
	v_mfma_f32_16x16x32_bf16 v[68:71], v[144:147], v[204:207], v[68:71]
	v_mfma_f32_16x16x32_bf16 v[4:7], v[152:155], v[204:207], v[4:7]
	v_mfma_f32_16x16x32_bf16 v[64:67], v[144:147], v[212:215], v[64:67]
	v_mfma_f32_16x16x32_bf16 v[0:3], v[152:155], v[212:215], v[0:3]
	v_mfma_f32_16x16x32_bf16 v[88:91], v[148:151], v[192:195], v[88:91]
	v_mfma_f32_16x16x32_bf16 v[20:23], v[156:159], v[192:195], v[20:23]
	v_mfma_f32_16x16x32_bf16 v[80:83], v[148:151], v[200:203], v[80:83]
	v_mfma_f32_16x16x32_bf16 v[16:19], v[156:159], v[200:203], v[16:19]
	v_mfma_f32_16x16x32_bf16 v[68:71], v[148:151], v[208:211], v[68:71]
	v_mfma_f32_16x16x32_bf16 v[4:7], v[156:159], v[208:211], v[4:7]
	v_mfma_f32_16x16x32_bf16 v[64:67], v[148:151], v[216:219], v[64:67]
	v_mfma_f32_16x16x32_bf16 v[0:3], v[156:159], v[216:219], v[0:3]
	s_barrier
	s_add_i32 s96, s96, 2
	s_add_u32 s35, s35, 0x100
	s_addc_u32 s49, s49, 0
	s_cmp_gt_u32 s96, 61
	s_mov_b64 s[50:51], s[52:53]
	s_cbranch_scc0 .LBB0_914
	s_setprio 0
	s_lshl_b32 s34, s46, 2
	v_lshl_or_b32 v178, s48, 7, v186
	s_add_i32 s34, s34, s65
	v_ashrrev_i32_e32 v179, 31, v178
	s_mul_hi_i32 s35, s34, 0x30000
	s_mul_i32 s39, s34, 0x30000
	s_and_saveexec_b64 s[48:49], s[0:1]
	s_cbranch_execz .LBB0_917
	s_add_u32 s50, s79, s39
	s_addc_u32 s51, s81, s35
	v_lshl_add_u64 v[132:133], v[178:179], 1, s[50:51]
	v_add_co_u32_e32 v134, vcc, s78, v132
	s_nop 2
	v_cvt_pk_bf16_f32 v128, v124, v125
	s_nop 2
	v_cvt_pk_bf16_f32 v129, v126, v127
	s_nop 2
	v_cvt_pk_bf16_f32 v130, v60, v61
	s_nop 2
	v_cvt_pk_bf16_f32 v131, v62, v63
	s_nop 1
	v_addc_co_u32_e32 v135, vcc, 0, v133, vcc
	s_mov_b32 s17, 0xc000
	global_store_dwordx4 v[132:133], v[128:131], off
	s_nop 1
	s_nop 2
	v_cvt_pk_bf16_f32 v128, v120, v121
	s_nop 2
	v_cvt_pk_bf16_f32 v129, v122, v123
	s_nop 2
	v_cvt_pk_bf16_f32 v130, v52, v53
	s_nop 2
	v_cvt_pk_bf16_f32 v131, v54, v55
	global_store_dwordx4 v[134:135], v[128:131], off
	v_add_co_u32_e32 v134, vcc, s17, v132
	s_nop 0
	s_nop 2
	v_cvt_pk_bf16_f32 v128, v116, v117
	s_nop 2
	v_cvt_pk_bf16_f32 v129, v118, v119
	s_nop 2
	v_cvt_pk_bf16_f32 v130, v56, v57
	s_nop 2
	v_cvt_pk_bf16_f32 v131, v58, v59
	s_nop 0
	v_addc_co_u32_e32 v135, vcc, 0, v133, vcc
	v_add_co_u32_e32 v132, vcc, 0x12000, v132
	global_store_dwordx4 v[134:135], v[128:131], off
	s_nop 0
	v_addc_co_u32_e32 v133, vcc, 0, v133, vcc
	s_nop 2
	v_cvt_pk_bf16_f32 v128, v112, v113
	s_nop 2
	v_cvt_pk_bf16_f32 v129, v114, v115
	s_nop 2
	v_cvt_pk_bf16_f32 v130, v48, v49
	s_nop 2
	v_cvt_pk_bf16_f32 v131, v50, v51
	global_store_dwordx4 v[132:133], v[128:131], off

.Lmy_prio_skip6:
.LBB0_1077:
	ds_read_b128 v[144:147], v153
	ds_read_b128 v[156:159], v153 offset:1024
	ds_read_b128 v[160:163], v153 offset:2048
	ds_read_b128 v[164:167], v153 offset:3072
	ds_read_b128 v[168:171], v154
	ds_read_b128 v[172:175], v154 offset:1024
	ds_read_b128 v[176:179], v154 offset:2048
	ds_read_b128 v[180:183], v154 offset:3072
	s_add_u32 s28, s26, 0x100
	s_addc_u32 s29, s27, 0
	s_cmpk_eq_i32 s53, 0xbc
	s_cselect_b32 s37, s3, s29
	s_cselect_b32 s36, s2, s28
	s_cselect_b32 s31, s25, s35
	s_cselect_b32 s30, s24, s34
	s_add_i32 m0, s39, 0xc000
	ds_read_b128 v[184:187], v155
	ds_read_b128 v[188:191], v155 offset:1024
	ds_read_b128 v[192:195], v155 offset:2048
	ds_read_b128 v[196:199], v155 offset:3072
	ds_read_b128 v[200:203], v155 offset:4096
	ds_read_b128 v[204:207], v155 offset:5120
	ds_read_b128 v[208:211], v155 offset:6144
	ds_read_b128 v[212:215], v155 offset:7168
	global_load_lds_dwordx4 v136, s[26:27]
	s_add_i32 m0, s39, 0xe000
	s_nop 0
	global_load_lds_dwordx4 v138, s[26:27]
	s_waitcnt vmcnt(8)
	s_waitcnt lgkmcnt(0)
	s_barrier
	s_waitcnt lgkmcnt(0)
	v_mfma_f32_16x16x32_bf16 v[124:127], v[144:147], v[184:187], v[124:127]
	v_mfma_f32_16x16x32_bf16 v[120:123], v[160:163], v[184:187], v[120:123]
	v_mfma_f32_16x16x32_bf16 v[108:111], v[144:147], v[192:195], v[108:111]
	v_mfma_f32_16x16x32_bf16 v[104:107], v[160:163], v[192:195], v[104:107]
	v_mfma_f32_16x16x32_bf16 v[92:95], v[144:147], v[200:203], v[92:95]
	v_mfma_f32_16x16x32_bf16 v[88:91], v[160:163], v[200:203], v[88:91]
	v_mfma_f32_16x16x32_bf16 v[76:79], v[144:147], v[208:211], v[76:79]
	v_mfma_f32_16x16x32_bf16 v[72:75], v[160:163], v[208:211], v[72:75]
	v_mfma_f32_16x16x32_bf16 v[124:127], v[156:159], v[188:191], v[124:127]
	v_mfma_f32_16x16x32_bf16 v[120:123], v[164:167], v[188:191], v[120:123]
	v_mfma_f32_16x16x32_bf16 v[108:111], v[156:159], v[196:199], v[108:111]
	v_mfma_f32_16x16x32_bf16 v[104:107], v[164:167], v[196:199], v[104:107]
	v_mfma_f32_16x16x32_bf16 v[92:95], v[156:159], v[204:207], v[92:95]
	v_mfma_f32_16x16x32_bf16 v[88:91], v[164:167], v[204:207], v[88:91]
	v_mfma_f32_16x16x32_bf16 v[76:79], v[156:159], v[212:215], v[76:79]
	v_mfma_f32_16x16x32_bf16 v[72:75], v[164:167], v[212:215], v[72:75]
	v_mfma_f32_16x16x32_bf16 v[116:119], v[168:171], v[184:187], v[116:119]
	v_mfma_f32_16x16x32_bf16 v[112:115], v[176:179], v[184:187], v[112:115]
	v_mfma_f32_16x16x32_bf16 v[100:103], v[168:171], v[192:195], v[100:103]
	v_mfma_f32_16x16x32_bf16 v[96:99], v[176:179], v[192:195], v[96:99]
	v_mfma_f32_16x16x32_bf16 v[84:87], v[168:171], v[200:203], v[84:87]
	v_mfma_f32_16x16x32_bf16 v[80:83], v[176:179], v[200:203], v[80:83]
	v_mfma_f32_16x16x32_bf16 v[68:71], v[168:171], v[208:211], v[68:71]
	v_mfma_f32_16x16x32_bf16 v[64:67], v[176:179], v[208:211], v[64:67]
	v_mfma_f32_16x16x32_bf16 v[116:119], v[172:175], v[188:191], v[116:119]
	v_mfma_f32_16x16x32_bf16 v[112:115], v[180:183], v[188:191], v[112:115]
	v_mfma_f32_16x16x32_bf16 v[100:103], v[172:175], v[196:199], v[100:103]
	v_mfma_f32_16x16x32_bf16 v[96:99], v[180:183], v[196:199], v[96:99]
	v_mfma_f32_16x16x32_bf16 v[84:87], v[172:175], v[204:207], v[84:87]
	v_mfma_f32_16x16x32_bf16 v[80:83], v[180:183], v[204:207], v[80:83]
	v_mfma_f32_16x16x32_bf16 v[68:71], v[172:175], v[212:215], v[68:71]
	v_mfma_f32_16x16x32_bf16 v[64:67], v[180:183], v[212:215], v[64:67]
	s_barrier
	s_add_i32 s26, s47, s38
	s_mov_b32 m0, s26
	ds_read_b128 v[184:187], v155 offset:16384
	ds_read_b128 v[188:191], v155 offset:17408
	ds_read_b128 v[192:195], v155 offset:18432
	ds_read_b128 v[196:199], v155 offset:19456
	ds_read_b128 v[200:203], v155 offset:20480
	ds_read_b128 v[204:207], v155 offset:21504
	ds_read_b128 v[208:211], v155 offset:22528
	ds_read_b128 v[212:215], v155 offset:23552
	global_load_lds_dwordx4 v130, s[30:31]
	s_add_i32 m0, s26, 0x2000
	s_add_u32 s26, s30, 0x300000
	v_lshl_add_u64 v[216:217], s[30:31], 0, v[134:135]
	s_addc_u32 s27, s31, 0
	s_add_i32 s54, s48, s38
	global_load_lds_dwordx4 v134, s[30:31]
	s_mov_b32 m0, s54
	global_load_lds_dwordx4 v130, s[26:27]
	s_add_i32 m0, s54, 0x2000
	s_nop 0
	global_load_lds_dwordx4 v134, s[26:27]
	s_mov_b32 m0, s39
	s_nop 0
	global_load_lds_dwordx4 v128, s[36:37]
	s_mov_b32 m0, s40
	s_nop 0
	global_load_lds_dwordx4 v132, s[36:37]
	s_waitcnt vmcnt(8)
	s_waitcnt lgkmcnt(0)
	s_barrier
	s_waitcnt lgkmcnt(0)
	v_mfma_f32_16x16x32_bf16 v[60:63], v[144:147], v[184:187], v[60:63]
	v_mfma_f32_16x16x32_bf16 v[56:59], v[160:163], v[184:187], v[56:59]
	v_mfma_f32_16x16x32_bf16 v[44:47], v[144:147], v[192:195], v[44:47]
	v_mfma_f32_16x16x32_bf16 v[40:43], v[160:163], v[192:195], v[40:43]
	v_mfma_f32_16x16x32_bf16 v[28:31], v[144:147], v[200:203], v[28:31]
	v_mfma_f32_16x16x32_bf16 v[24:27], v[160:163], v[200:203], v[24:27]
	v_mfma_f32_16x16x32_bf16 v[12:15], v[144:147], v[208:211], v[12:15]
	v_mfma_f32_16x16x32_bf16 v[8:11], v[160:163], v[208:211], v[8:11]
	v_mfma_f32_16x16x32_bf16 v[60:63], v[156:159], v[188:191], v[60:63]
	v_mfma_f32_16x16x32_bf16 v[56:59], v[164:167], v[188:191], v[56:59]
	v_mfma_f32_16x16x32_bf16 v[44:47], v[156:159], v[196:199], v[44:47]
	v_mfma_f32_16x16x32_bf16 v[40:43], v[164:167], v[196:199], v[40:43]
	v_mfma_f32_16x16x32_bf16 v[28:31], v[156:159], v[204:207], v[28:31]
	v_mfma_f32_16x16x32_bf16 v[24:27], v[164:167], v[204:207], v[24:27]
	v_mfma_f32_16x16x32_bf16 v[12:15], v[156:159], v[212:215], v[12:15]
	v_mfma_f32_16x16x32_bf16 v[8:11], v[164:167], v[212:215], v[8:11]
	v_mfma_f32_16x16x32_bf16 v[52:55], v[168:171], v[184:187], v[52:55]
	v_mfma_f32_16x16x32_bf16 v[48:51], v[176:179], v[184:187], v[48:51]
	v_mfma_f32_16x16x32_bf16 v[36:39], v[168:171], v[192:195], v[36:39]
	v_mfma_f32_16x16x32_bf16 v[32:35], v[176:179], v[192:195], v[32:35]
	v_mfma_f32_16x16x32_bf16 v[20:23], v[168:171], v[200:203], v[20:23]
	v_mfma_f32_16x16x32_bf16 v[16:19], v[176:179], v[200:203], v[16:19]
	v_mfma_f32_16x16x32_bf16 v[4:7], v[168:171], v[208:211], v[4:7]
	v_mfma_f32_16x16x32_bf16 v[0:3], v[176:179], v[208:211], v[0:3]
	v_mfma_f32_16x16x32_bf16 v[52:55], v[172:175], v[188:191], v[52:55]
	v_mfma_f32_16x16x32_bf16 v[48:51], v[180:183], v[188:191], v[48:51]
	v_mfma_f32_16x16x32_bf16 v[36:39], v[172:175], v[196:199], v[36:39]
	v_mfma_f32_16x16x32_bf16 v[32:35], v[180:183], v[196:199], v[32:35]
	v_mfma_f32_16x16x32_bf16 v[20:23], v[172:175], v[204:207], v[20:23]
	v_mfma_f32_16x16x32_bf16 v[16:19], v[180:183], v[204:207], v[16:19]
	v_mfma_f32_16x16x32_bf16 v[4:7], v[172:175], v[212:215], v[4:7]
	v_mfma_f32_16x16x32_bf16 v[0:3], v[180:183], v[212:215], v[0:3]
	s_barrier
	s_add_i32 s54, 0, 0x18000
	s_add_i32 s55, 0, 0x1c000
	v_add_u32_e32 v164, s54, v151
	v_add_u32_e32 v180, s55, v151
	ds_read_b128 v[144:147], v164
	ds_read_b128 v[156:159], v164 offset:1024
	ds_read_b128 v[160:163], v164 offset:2048
	ds_read_b128 v[164:167], v164 offset:3072
	ds_read_b128 v[168:171], v180
	ds_read_b128 v[172:175], v180 offset:1024
	ds_read_b128 v[176:179], v180 offset:2048
	ds_read_b128 v[180:183], v180 offset:3072
	s_add_u32 s26, s36, 0x300000
	s_addc_u32 s27, s37, 0
	s_mov_b32 m0, s41
	ds_read_b128 v[184:187], v155 offset:32768
	ds_read_b128 v[188:191], v155 offset:33792
	ds_read_b128 v[192:195], v155 offset:34816
	ds_read_b128 v[196:199], v155 offset:35840
	ds_read_b128 v[200:203], v155 offset:36864
	ds_read_b128 v[204:207], v155 offset:37888
	ds_read_b128 v[208:211], v155 offset:38912
	ds_read_b128 v[212:215], v155 offset:39936
	global_load_lds_dwordx4 v128, s[26:27]
	s_mov_b32 m0, s42
	s_nop 0
	global_load_lds_dwordx4 v132, s[26:27]
	s_waitcnt vmcnt(8)
	s_waitcnt lgkmcnt(0)
	s_barrier
	s_waitcnt lgkmcnt(0)
	v_mfma_f32_16x16x32_bf16 v[124:127], v[144:147], v[184:187], v[124:127]
	v_mfma_f32_16x16x32_bf16 v[120:123], v[160:163], v[184:187], v[120:123]
	v_mfma_f32_16x16x32_bf16 v[108:111], v[144:147], v[192:195], v[108:111]
	v_mfma_f32_16x16x32_bf16 v[104:107], v[160:163], v[192:195], v[104:107]
	v_mfma_f32_16x16x32_bf16 v[92:95], v[144:147], v[200:203], v[92:95]
	v_mfma_f32_16x16x32_bf16 v[88:91], v[160:163], v[200:203], v[88:91]
	v_mfma_f32_16x16x32_bf16 v[76:79], v[144:147], v[208:211], v[76:79]
	v_mfma_f32_16x16x32_bf16 v[72:75], v[160:163], v[208:211], v[72:75]
	v_mfma_f32_16x16x32_bf16 v[124:127], v[156:159], v[188:191], v[124:127]
	v_mfma_f32_16x16x32_bf16 v[120:123], v[164:167], v[188:191], v[120:123]
	v_mfma_f32_16x16x32_bf16 v[108:111], v[156:159], v[196:199], v[108:111]
	v_mfma_f32_16x16x32_bf16 v[104:107], v[164:167], v[196:199], v[104:107]
	v_mfma_f32_16x16x32_bf16 v[92:95], v[156:159], v[204:207], v[92:95]
	v_mfma_f32_16x16x32_bf16 v[88:91], v[164:167], v[204:207], v[88:91]
	v_mfma_f32_16x16x32_bf16 v[76:79], v[156:159], v[212:215], v[76:79]
	v_mfma_f32_16x16x32_bf16 v[72:75], v[164:167], v[212:215], v[72:75]
	v_mfma_f32_16x16x32_bf16 v[116:119], v[168:171], v[184:187], v[116:119]
	v_mfma_f32_16x16x32_bf16 v[112:115], v[176:179], v[184:187], v[112:115]
	v_mfma_f32_16x16x32_bf16 v[100:103], v[168:171], v[192:195], v[100:103]
	v_mfma_f32_16x16x32_bf16 v[96:99], v[176:179], v[192:195], v[96:99]
	v_mfma_f32_16x16x32_bf16 v[84:87], v[168:171], v[200:203], v[84:87]
	v_mfma_f32_16x16x32_bf16 v[80:83], v[176:179], v[200:203], v[80:83]
	v_mfma_f32_16x16x32_bf16 v[68:71], v[168:171], v[208:211], v[68:71]
	v_mfma_f32_16x16x32_bf16 v[64:67], v[176:179], v[208:211], v[64:67]
	v_mfma_f32_16x16x32_bf16 v[116:119], v[172:175], v[188:191], v[116:119]
	v_mfma_f32_16x16x32_bf16 v[112:115], v[180:183], v[188:191], v[112:115]
	v_mfma_f32_16x16x32_bf16 v[100:103], v[172:175], v[196:199], v[100:103]
	v_mfma_f32_16x16x32_bf16 v[96:99], v[180:183], v[196:199], v[96:99]
	v_mfma_f32_16x16x32_bf16 v[84:87], v[172:175], v[204:207], v[84:87]
	v_mfma_f32_16x16x32_bf16 v[80:83], v[180:183], v[204:207], v[80:83]
	v_mfma_f32_16x16x32_bf16 v[68:71], v[172:175], v[212:215], v[68:71]
	v_mfma_f32_16x16x32_bf16 v[64:67], v[180:183], v[212:215], v[64:67]
	s_barrier
	s_add_i32 s26, s54, s38
	s_mov_b32 m0, s26
	ds_read_b128 v[184:187], v155 offset:49152
	ds_read_b128 v[188:191], v155 offset:50176
	ds_read_b128 v[192:195], v155 offset:51200
	ds_read_b128 v[196:199], v155 offset:52224
	ds_read_b128 v[200:203], v155 offset:53248
	ds_read_b128 v[204:207], v155 offset:54272
	ds_read_b128 v[208:211], v155 offset:55296
	ds_read_b128 v[212:215], v155 offset:56320
	s_add_u32 vcc_lo, s30, 0x80
	s_addc_u32 vcc_hi, s31, 0
	global_load_lds_dwordx4 v130, vcc
	s_add_i32 m0, s26, 0x2000
	s_add_u32 s26, s30, 0x300080
	v_lshl_add_u64 v[148:149], v[216:217], 0, s[10:11]
	s_addc_u32 s27, s31, 0
	s_add_i32 s30, s55, s38
	global_load_lds_dwordx4 v[148:149], off
	s_mov_b32 m0, s30
	s_nop 0
	global_load_lds_dwordx4 v130, s[26:27]
	s_add_i32 m0, s30, 0x2000
	s_nop 0
	global_load_lds_dwordx4 v134, s[26:27]
	s_mov_b32 m0, s44
	s_nop 0
	s_add_u32 vcc_lo, s36, 0x80
	s_addc_u32 vcc_hi, s37, 0
	global_load_lds_dwordx4 v128, vcc
	s_mov_b32 m0, s45
	s_nop 0
	s_add_u32 vcc_lo, s36, 0x80
	s_addc_u32 vcc_hi, s37, 0
	global_load_lds_dwordx4 v132, vcc
	s_waitcnt vmcnt(8)
	s_waitcnt lgkmcnt(0)
	s_barrier
	s_waitcnt lgkmcnt(0)
	v_mfma_f32_16x16x32_bf16 v[60:63], v[144:147], v[184:187], v[60:63]
	v_mfma_f32_16x16x32_bf16 v[56:59], v[160:163], v[184:187], v[56:59]
	v_mfma_f32_16x16x32_bf16 v[44:47], v[144:147], v[192:195], v[44:47]
	v_mfma_f32_16x16x32_bf16 v[40:43], v[160:163], v[192:195], v[40:43]
	v_mfma_f32_16x16x32_bf16 v[28:31], v[144:147], v[200:203], v[28:31]
	v_mfma_f32_16x16x32_bf16 v[24:27], v[160:163], v[200:203], v[24:27]
	v_mfma_f32_16x16x32_bf16 v[12:15], v[144:147], v[208:211], v[12:15]
	v_mfma_f32_16x16x32_bf16 v[8:11], v[160:163], v[208:211], v[8:11]
	v_mfma_f32_16x16x32_bf16 v[60:63], v[156:159], v[188:191], v[60:63]
	v_mfma_f32_16x16x32_bf16 v[56:59], v[164:167], v[188:191], v[56:59]
	v_mfma_f32_16x16x32_bf16 v[44:47], v[156:159], v[196:199], v[44:47]
	v_mfma_f32_16x16x32_bf16 v[40:43], v[164:167], v[196:199], v[40:43]
	v_mfma_f32_16x16x32_bf16 v[28:31], v[156:159], v[204:207], v[28:31]
	v_mfma_f32_16x16x32_bf16 v[24:27], v[164:167], v[204:207], v[24:27]
	v_mfma_f32_16x16x32_bf16 v[12:15], v[156:159], v[212:215], v[12:15]
	v_mfma_f32_16x16x32_bf16 v[8:11], v[164:167], v[212:215], v[8:11]
	v_mfma_f32_16x16x32_bf16 v[52:55], v[168:171], v[184:187], v[52:55]
	v_mfma_f32_16x16x32_bf16 v[48:51], v[176:179], v[184:187], v[48:51]
	v_mfma_f32_16x16x32_bf16 v[36:39], v[168:171], v[192:195], v[36:39]
	v_mfma_f32_16x16x32_bf16 v[32:35], v[176:179], v[192:195], v[32:35]
	v_mfma_f32_16x16x32_bf16 v[20:23], v[168:171], v[200:203], v[20:23]
	v_mfma_f32_16x16x32_bf16 v[16:19], v[176:179], v[200:203], v[16:19]
	v_mfma_f32_16x16x32_bf16 v[4:7], v[168:171], v[208:211], v[4:7]
	v_mfma_f32_16x16x32_bf16 v[0:3], v[176:179], v[208:211], v[0:3]
	v_mfma_f32_16x16x32_bf16 v[52:55], v[172:175], v[188:191], v[52:55]
	v_mfma_f32_16x16x32_bf16 v[48:51], v[180:183], v[188:191], v[48:51]
	v_mfma_f32_16x16x32_bf16 v[36:39], v[172:175], v[196:199], v[36:39]
	v_mfma_f32_16x16x32_bf16 v[32:35], v[180:183], v[196:199], v[32:35]
	v_mfma_f32_16x16x32_bf16 v[20:23], v[172:175], v[204:207], v[20:23]
	v_mfma_f32_16x16x32_bf16 v[16:19], v[180:183], v[204:207], v[16:19]
	v_mfma_f32_16x16x32_bf16 v[4:7], v[172:175], v[212:215], v[4:7]
	v_mfma_f32_16x16x32_bf16 v[0:3], v[180:183], v[212:215], v[0:3]
	s_barrier
	s_add_i32 s53, s53, 2
	s_add_u32 s34, s34, 0x100
	s_addc_u32 s35, s35, 0
	s_cmpk_gt_u32 s53, 0xbd
	s_mov_b64 s[26:27], s[28:29]
	s_cbranch_scc0 .LBB0_1077
	s_setprio 0
	s_and_b64 vcc, exec, s[12:13]
	s_cbranch_vccz .LBB0_1080
	s_barrier

.Lmy_prio_skip7:
.LBB0_1313:
	ds_read_b128 v[48:51], v163
	ds_read_b128 v[52:55], v163 offset:1024
	ds_read_b128 v[152:155], v163 offset:2048
	ds_read_b128 v[156:159], v163 offset:3072
	ds_read_b128 v[168:171], v164
	ds_read_b128 v[172:175], v164 offset:1024
	ds_read_b128 v[176:179], v164 offset:2048
	ds_read_b128 v[180:183], v164 offset:3072
	s_add_u32 s42, s40, 0xfff00080
	s_addc_u32 s43, s41, -1
	s_cmp_eq_u32 s60, 60
	s_cselect_b32 s45, s14, s43
	s_cselect_b32 s44, s29, s42
	s_cselect_b32 s43, s27, s35
	s_cselect_b32 s42, s39, s34
	s_add_i32 m0, s47, 0xc000
	ds_read_b128 v[184:187], v165
	ds_read_b128 v[188:191], v165 offset:1024
	ds_read_b128 v[192:195], v165 offset:2048
	ds_read_b128 v[196:199], v165 offset:3072
	ds_read_b128 v[200:203], v165 offset:4096
	ds_read_b128 v[204:207], v165 offset:5120
	ds_read_b128 v[208:211], v165 offset:6144
	ds_read_b128 v[212:215], v165 offset:7168
	global_load_lds_dwordx4 v144, s[40:41]
	s_add_i32 m0, s47, 0xe000
	s_nop 0
	global_load_lds_dwordx4 v146, s[40:41]
	s_waitcnt vmcnt(8)
	s_waitcnt lgkmcnt(0)
	s_barrier
	s_waitcnt lgkmcnt(0)
	v_mfma_f32_16x16x32_bf16 v[44:47], v[48:51], v[184:187], v[44:47]
	v_mfma_f32_16x16x32_bf16 v[40:43], v[152:155], v[184:187], v[40:43]
	v_mfma_f32_16x16x32_bf16 v[124:127], v[48:51], v[192:195], v[124:127]
	v_mfma_f32_16x16x32_bf16 v[120:123], v[152:155], v[192:195], v[120:123]
	v_mfma_f32_16x16x32_bf16 v[108:111], v[48:51], v[200:203], v[108:111]
	v_mfma_f32_16x16x32_bf16 v[104:107], v[152:155], v[200:203], v[104:107]
	v_mfma_f32_16x16x32_bf16 v[92:95], v[48:51], v[208:211], v[92:95]
	v_mfma_f32_16x16x32_bf16 v[88:91], v[152:155], v[208:211], v[88:91]
	v_mfma_f32_16x16x32_bf16 v[44:47], v[52:55], v[188:191], v[44:47]
	v_mfma_f32_16x16x32_bf16 v[40:43], v[156:159], v[188:191], v[40:43]
	v_mfma_f32_16x16x32_bf16 v[124:127], v[52:55], v[196:199], v[124:127]
	v_mfma_f32_16x16x32_bf16 v[120:123], v[156:159], v[196:199], v[120:123]
	v_mfma_f32_16x16x32_bf16 v[108:111], v[52:55], v[204:207], v[108:111]
	v_mfma_f32_16x16x32_bf16 v[104:107], v[156:159], v[204:207], v[104:107]
	v_mfma_f32_16x16x32_bf16 v[92:95], v[52:55], v[212:215], v[92:95]
	v_mfma_f32_16x16x32_bf16 v[88:91], v[156:159], v[212:215], v[88:91]
	v_mfma_f32_16x16x32_bf16 v[132:135], v[168:171], v[184:187], v[132:135]
	v_mfma_f32_16x16x32_bf16 v[128:131], v[176:179], v[184:187], v[128:131]
	v_mfma_f32_16x16x32_bf16 v[116:119], v[168:171], v[192:195], v[116:119]
	v_mfma_f32_16x16x32_bf16 v[112:115], v[176:179], v[192:195], v[112:115]
	v_mfma_f32_16x16x32_bf16 v[100:103], v[168:171], v[200:203], v[100:103]
	v_mfma_f32_16x16x32_bf16 v[96:99], v[176:179], v[200:203], v[96:99]
	v_mfma_f32_16x16x32_bf16 v[84:87], v[168:171], v[208:211], v[84:87]
	v_mfma_f32_16x16x32_bf16 v[80:83], v[176:179], v[208:211], v[80:83]
	v_mfma_f32_16x16x32_bf16 v[132:135], v[172:175], v[188:191], v[132:135]
	v_mfma_f32_16x16x32_bf16 v[128:131], v[180:183], v[188:191], v[128:131]
	v_mfma_f32_16x16x32_bf16 v[116:119], v[172:175], v[196:199], v[116:119]
	v_mfma_f32_16x16x32_bf16 v[112:115], v[180:183], v[196:199], v[112:115]
	v_mfma_f32_16x16x32_bf16 v[100:103], v[172:175], v[204:207], v[100:103]
	v_mfma_f32_16x16x32_bf16 v[96:99], v[180:183], v[204:207], v[96:99]
	v_mfma_f32_16x16x32_bf16 v[84:87], v[172:175], v[212:215], v[84:87]
	v_mfma_f32_16x16x32_bf16 v[80:83], v[180:183], v[212:215], v[80:83]
	s_barrier
	s_add_i32 s61, s56, s46
	s_mov_b32 m0, s61
	ds_read_b128 v[184:187], v165 offset:16384
	ds_read_b128 v[188:191], v165 offset:17408
	ds_read_b128 v[192:195], v165 offset:18432
	ds_read_b128 v[196:199], v165 offset:19456
	ds_read_b128 v[200:203], v165 offset:20480
	ds_read_b128 v[204:207], v165 offset:21504
	ds_read_b128 v[208:211], v165 offset:22528
	ds_read_b128 v[212:215], v165 offset:23552
	global_load_lds_dwordx4 v138, s[42:43]
	s_add_i32 m0, s61, 0x2000
	s_add_u32 s62, s42, 0x100000
	v_lshl_add_u64 v[218:219], s[42:43], 0, v[142:143]
	s_addc_u32 s63, s43, 0
	s_add_i32 s61, s57, s46
	global_load_lds_dwordx4 v142, s[42:43]
	s_mov_b32 m0, s61
	v_lshl_add_u64 v[222:223], s[44:45], 0, v[140:141]
	global_load_lds_dwordx4 v138, s[62:63]
	s_add_i32 m0, s61, 0x2000
	s_nop 0
	global_load_lds_dwordx4 v142, s[62:63]
	v_lshl_add_u64 v[220:221], s[44:45], 0, v[136:137]
	s_mov_b32 m0, s47
	s_nop 0
	global_load_lds_dwordx4 v136, s[44:45]
	s_mov_b32 m0, s48
	s_nop 0
	global_load_lds_dwordx4 v140, s[44:45]
	s_waitcnt vmcnt(8)
	s_waitcnt lgkmcnt(0)
	s_barrier
	s_waitcnt lgkmcnt(0)
	v_mfma_f32_16x16x32_bf16 v[76:79], v[48:51], v[184:187], v[76:79]
	v_mfma_f32_16x16x32_bf16 v[72:75], v[152:155], v[184:187], v[72:75]
	v_mfma_f32_16x16x32_bf16 v[60:63], v[48:51], v[192:195], v[60:63]
	v_mfma_f32_16x16x32_bf16 v[56:59], v[152:155], v[192:195], v[56:59]
	v_mfma_f32_16x16x32_bf16 v[28:31], v[48:51], v[200:203], v[28:31]
	v_mfma_f32_16x16x32_bf16 v[24:27], v[152:155], v[200:203], v[24:27]
	v_mfma_f32_16x16x32_bf16 v[12:15], v[48:51], v[208:211], v[12:15]
	v_mfma_f32_16x16x32_bf16 v[8:11], v[152:155], v[208:211], v[8:11]
	v_mfma_f32_16x16x32_bf16 v[76:79], v[52:55], v[188:191], v[76:79]
	v_mfma_f32_16x16x32_bf16 v[72:75], v[156:159], v[188:191], v[72:75]
	v_mfma_f32_16x16x32_bf16 v[60:63], v[52:55], v[196:199], v[60:63]
	v_mfma_f32_16x16x32_bf16 v[56:59], v[156:159], v[196:199], v[56:59]
	v_mfma_f32_16x16x32_bf16 v[28:31], v[52:55], v[204:207], v[28:31]
	v_mfma_f32_16x16x32_bf16 v[24:27], v[156:159], v[204:207], v[24:27]
	v_mfma_f32_16x16x32_bf16 v[12:15], v[52:55], v[212:215], v[12:15]
	v_mfma_f32_16x16x32_bf16 v[8:11], v[156:159], v[212:215], v[8:11]
	v_mfma_f32_16x16x32_bf16 v[36:39], v[168:171], v[192:195], v[36:39]
	v_mfma_f32_16x16x32_bf16 v[32:35], v[176:179], v[192:195], v[32:35]
	v_mfma_f32_16x16x32_bf16 v[20:23], v[168:171], v[200:203], v[20:23]
	v_mfma_f32_16x16x32_bf16 v[16:19], v[176:179], v[200:203], v[16:19]
	v_mfma_f32_16x16x32_bf16 v[4:7], v[168:171], v[208:211], v[4:7]
	v_mfma_f32_16x16x32_bf16 v[0:3], v[176:179], v[208:211], v[0:3]
	v_mfma_f32_16x16x32_bf16 v[48:51], v[168:171], v[184:187], v[68:71]
	v_mfma_f32_16x16x32_bf16 v[52:55], v[176:179], v[184:187], v[64:67]
	v_mfma_f32_16x16x32_bf16 v[36:39], v[172:175], v[196:199], v[36:39]
	v_mfma_f32_16x16x32_bf16 v[32:35], v[180:183], v[196:199], v[32:35]
	v_mfma_f32_16x16x32_bf16 v[20:23], v[172:175], v[204:207], v[20:23]
	v_mfma_f32_16x16x32_bf16 v[16:19], v[180:183], v[204:207], v[16:19]
	v_mfma_f32_16x16x32_bf16 v[4:7], v[172:175], v[212:215], v[4:7]
	v_mfma_f32_16x16x32_bf16 v[0:3], v[180:183], v[212:215], v[0:3]
	v_mfma_f32_16x16x32_bf16 v[48:51], v[172:175], v[188:191], v[48:51]
	v_mfma_f32_16x16x32_bf16 v[52:55], v[180:183], v[188:191], v[52:55]
	s_barrier
	s_add_i32 s61, 0, 0x18000
	s_add_i32 s62, 0, 0x1c000
	v_add_u32_e32 v156, s61, v161
	v_add_u32_e32 v167, s62, v161
	ds_read_b128 v[64:67], v156
	ds_read_b128 v[68:71], v156 offset:1024
	ds_read_b128 v[152:155], v156 offset:2048
	ds_read_b128 v[156:159], v156 offset:3072
	ds_read_b128 v[168:171], v167
	ds_read_b128 v[172:175], v167 offset:1024
	ds_read_b128 v[176:179], v167 offset:2048
	ds_read_b128 v[180:183], v167 offset:3072
	s_add_u32 s44, s44, 0x100000
	s_addc_u32 s45, s45, 0
	s_mov_b32 m0, s49
	ds_read_b128 v[184:187], v165 offset:32768
	ds_read_b128 v[188:191], v165 offset:33792
	ds_read_b128 v[192:195], v165 offset:34816
	ds_read_b128 v[196:199], v165 offset:35840
	ds_read_b128 v[200:203], v165 offset:36864
	ds_read_b128 v[204:207], v165 offset:37888
	ds_read_b128 v[208:211], v165 offset:38912
	ds_read_b128 v[212:215], v165 offset:39936
	global_load_lds_dwordx4 v136, s[44:45]
	s_mov_b32 m0, s50
	s_nop 0
	global_load_lds_dwordx4 v140, s[44:45]
	s_waitcnt vmcnt(8)
	s_waitcnt lgkmcnt(0)
	s_barrier
	s_waitcnt lgkmcnt(0)
	v_mfma_f32_16x16x32_bf16 v[44:47], v[64:67], v[184:187], v[44:47]
	v_mfma_f32_16x16x32_bf16 v[40:43], v[152:155], v[184:187], v[40:43]
	v_mfma_f32_16x16x32_bf16 v[124:127], v[64:67], v[192:195], v[124:127]
	v_mfma_f32_16x16x32_bf16 v[120:123], v[152:155], v[192:195], v[120:123]
	v_mfma_f32_16x16x32_bf16 v[108:111], v[64:67], v[200:203], v[108:111]
	v_mfma_f32_16x16x32_bf16 v[104:107], v[152:155], v[200:203], v[104:107]
	v_mfma_f32_16x16x32_bf16 v[92:95], v[64:67], v[208:211], v[92:95]
	v_mfma_f32_16x16x32_bf16 v[88:91], v[152:155], v[208:211], v[88:91]
	v_mfma_f32_16x16x32_bf16 v[44:47], v[68:71], v[188:191], v[44:47]
	v_mfma_f32_16x16x32_bf16 v[40:43], v[156:159], v[188:191], v[40:43]
	v_mfma_f32_16x16x32_bf16 v[124:127], v[68:71], v[196:199], v[124:127]
	v_mfma_f32_16x16x32_bf16 v[120:123], v[156:159], v[196:199], v[120:123]
	v_mfma_f32_16x16x32_bf16 v[108:111], v[68:71], v[204:207], v[108:111]
	v_mfma_f32_16x16x32_bf16 v[104:107], v[156:159], v[204:207], v[104:107]
	v_mfma_f32_16x16x32_bf16 v[92:95], v[68:71], v[212:215], v[92:95]
	v_mfma_f32_16x16x32_bf16 v[88:91], v[156:159], v[212:215], v[88:91]
	v_mfma_f32_16x16x32_bf16 v[132:135], v[168:171], v[184:187], v[132:135]
	v_mfma_f32_16x16x32_bf16 v[128:131], v[176:179], v[184:187], v[128:131]
	v_mfma_f32_16x16x32_bf16 v[116:119], v[168:171], v[192:195], v[116:119]
	v_mfma_f32_16x16x32_bf16 v[112:115], v[176:179], v[192:195], v[112:115]
	v_mfma_f32_16x16x32_bf16 v[100:103], v[168:171], v[200:203], v[100:103]
	v_mfma_f32_16x16x32_bf16 v[96:99], v[176:179], v[200:203], v[96:99]
	v_mfma_f32_16x16x32_bf16 v[84:87], v[168:171], v[208:211], v[84:87]
	v_mfma_f32_16x16x32_bf16 v[80:83], v[176:179], v[208:211], v[80:83]
	v_mfma_f32_16x16x32_bf16 v[132:135], v[172:175], v[188:191], v[132:135]
	v_mfma_f32_16x16x32_bf16 v[128:131], v[180:183], v[188:191], v[128:131]
	v_mfma_f32_16x16x32_bf16 v[116:119], v[172:175], v[196:199], v[116:119]
	v_mfma_f32_16x16x32_bf16 v[112:115], v[180:183], v[196:199], v[112:115]
	v_mfma_f32_16x16x32_bf16 v[100:103], v[172:175], v[204:207], v[100:103]
	v_mfma_f32_16x16x32_bf16 v[96:99], v[180:183], v[204:207], v[96:99]
	v_mfma_f32_16x16x32_bf16 v[84:87], v[172:175], v[212:215], v[84:87]
	v_mfma_f32_16x16x32_bf16 v[80:83], v[180:183], v[212:215], v[80:83]
	s_barrier
	s_add_i32 s44, s61, s46
	s_mov_b32 m0, s44
	ds_read_b128 v[184:187], v165 offset:49152
	ds_read_b128 v[188:191], v165 offset:50176
	ds_read_b128 v[192:195], v165 offset:51200
	ds_read_b128 v[196:199], v165 offset:52224
	ds_read_b128 v[200:203], v165 offset:53248
	ds_read_b128 v[204:207], v165 offset:54272
	ds_read_b128 v[208:211], v165 offset:55296
	ds_read_b128 v[212:215], v165 offset:56320
	s_add_u32 vcc_lo, s42, 0x80
	s_addc_u32 vcc_hi, s43, 0
	global_load_lds_dwordx4 v138, vcc
	s_add_i32 m0, s44, 0x2000
	s_add_u32 s42, s42, 0x100080
	v_lshl_add_u64 v[216:217], v[218:219], 0, s[22:23]
	s_addc_u32 s43, s43, 0
	s_add_i32 s44, s62, s46
	global_load_lds_dwordx4 v[216:217], off
	s_mov_b32 m0, s44
	s_nop 0
	global_load_lds_dwordx4 v138, s[42:43]
	s_add_i32 m0, s44, 0x2000
	s_nop 0
	global_load_lds_dwordx4 v142, s[42:43]
	v_lshl_add_u64 v[216:217], v[220:221], 0, s[22:23]
	s_mov_b32 m0, s52
	s_nop 0
	global_load_lds_dwordx4 v[216:217], off
	v_lshl_add_u64 v[216:217], v[222:223], 0, s[22:23]
	s_mov_b32 m0, s53
	s_nop 0
	global_load_lds_dwordx4 v[216:217], off
	s_waitcnt vmcnt(8)
	s_waitcnt lgkmcnt(0)
	s_barrier
	s_waitcnt lgkmcnt(0)
	v_mfma_f32_16x16x32_bf16 v[76:79], v[64:67], v[184:187], v[76:79]
	v_mfma_f32_16x16x32_bf16 v[72:75], v[152:155], v[184:187], v[72:75]
	v_mfma_f32_16x16x32_bf16 v[60:63], v[64:67], v[192:195], v[60:63]
	v_mfma_f32_16x16x32_bf16 v[56:59], v[152:155], v[192:195], v[56:59]
	v_mfma_f32_16x16x32_bf16 v[28:31], v[64:67], v[200:203], v[28:31]
	v_mfma_f32_16x16x32_bf16 v[24:27], v[152:155], v[200:203], v[24:27]
	v_mfma_f32_16x16x32_bf16 v[12:15], v[64:67], v[208:211], v[12:15]
	v_mfma_f32_16x16x32_bf16 v[8:11], v[152:155], v[208:211], v[8:11]
	v_mfma_f32_16x16x32_bf16 v[76:79], v[68:71], v[188:191], v[76:79]
	v_mfma_f32_16x16x32_bf16 v[72:75], v[156:159], v[188:191], v[72:75]
	v_mfma_f32_16x16x32_bf16 v[60:63], v[68:71], v[196:199], v[60:63]
	v_mfma_f32_16x16x32_bf16 v[56:59], v[156:159], v[196:199], v[56:59]
	v_mfma_f32_16x16x32_bf16 v[28:31], v[68:71], v[204:207], v[28:31]
	v_mfma_f32_16x16x32_bf16 v[24:27], v[156:159], v[204:207], v[24:27]
	v_mfma_f32_16x16x32_bf16 v[12:15], v[68:71], v[212:215], v[12:15]
	v_mfma_f32_16x16x32_bf16 v[8:11], v[156:159], v[212:215], v[8:11]
	v_mfma_f32_16x16x32_bf16 v[48:51], v[168:171], v[184:187], v[48:51]
	v_mfma_f32_16x16x32_bf16 v[68:71], v[172:175], v[188:191], v[48:51]
	v_mfma_f32_16x16x32_bf16 v[48:51], v[176:179], v[184:187], v[52:55]
	v_mfma_f32_16x16x32_bf16 v[36:39], v[168:171], v[192:195], v[36:39]
	v_mfma_f32_16x16x32_bf16 v[32:35], v[176:179], v[192:195], v[32:35]
	v_mfma_f32_16x16x32_bf16 v[20:23], v[168:171], v[200:203], v[20:23]
	v_mfma_f32_16x16x32_bf16 v[16:19], v[176:179], v[200:203], v[16:19]
	v_mfma_f32_16x16x32_bf16 v[4:7], v[168:171], v[208:211], v[4:7]
	v_mfma_f32_16x16x32_bf16 v[0:3], v[176:179], v[208:211], v[0:3]
	v_mfma_f32_16x16x32_bf16 v[64:67], v[180:183], v[188:191], v[48:51]
	v_mfma_f32_16x16x32_bf16 v[36:39], v[172:175], v[196:199], v[36:39]
	v_mfma_f32_16x16x32_bf16 v[32:35], v[180:183], v[196:199], v[32:35]
	v_mfma_f32_16x16x32_bf16 v[20:23], v[172:175], v[204:207], v[20:23]
	v_mfma_f32_16x16x32_bf16 v[16:19], v[180:183], v[204:207], v[16:19]
	v_mfma_f32_16x16x32_bf16 v[4:7], v[172:175], v[212:215], v[4:7]
	v_mfma_f32_16x16x32_bf16 v[0:3], v[180:183], v[212:215], v[0:3]
	s_barrier
	s_add_i32 s60, s60, 2
	s_add_u32 s40, s40, 0x100
	s_addc_u32 s41, s41, 0
	s_add_u32 s34, s34, 0x100
	s_addc_u32 s35, s35, 0
	s_cmp_gt_u32 s60, 61
	s_cbranch_scc0 .LBB0_1313
	s_setprio 0
	s_and_b64 vcc, exec, s[24:25]
	s_cbranch_vccz .LBB0_1316
	s_barrier
